# all s_setprio removed from the GEMM K-loops (A/B: are the per-phase priority flips load-bearing here)
# baseline (speedup 1.0000x reference)
; #define PG8_STAGE(bufoff, gbase, voff) do { _Pragma("unroll") for (int _i = 0; _i < 2; ++_i) \
;         __builtin_amdgcn_global_load_lds((const unsigned*)((const char*)(gbase) + (voff)[_i]), (PG8_LAS unsigned*)(lds + (bufoff) + ldsw + _i * 8192), 16, 0, 0); } while (0)
; #define PG8_LDA(dst, b, h) do { _Pragma("unroll") for (int m = 0; m < 4; ++m) _Pragma("unroll") for (int k = 0; k < 2; ++k) dst[m][k] = *(const PG8_LAS bf16x8*)(lds + PG8_SA(b, h) + aoff + m * 2048 + k * 1024); } while (0)
; #define PG8_LDB(dst, b, h) do { _Pragma("unroll") for (int n = 0; n < 2; ++n) _Pragma("unroll") for (int k = 0; k < 2; ++k) dst[n][k] = *(const PG8_LAS bf16x8*)(lds + PG8_SB(b, h) + boff + n * 2048 + k * 1024); } while (0)
; #define PG8_MMA(ai, bj, At, Bt) do { __builtin_amdgcn_s_setprio(1); _Pragma("unroll") for (int m = 0; m < 4; ++m) _Pragma("unroll") for (int n = 0; n < 2; ++n) _Pragma("unroll") for (int k = 0; k < 2; ++k) \
;         acc[ai][bj][m][n] = __builtin_amdgcn_mfma_f32_16x16x32_bf16(Bt[n][k], At[m][k], acc[ai][bj][m][n], 0, 0, 0); __builtin_amdgcn_s_setprio(0); } while (0)
; #define PG8_WAIT_V(n) asm volatile("s_waitcnt vmcnt(" #n ")" ::: "memory")
; #define PG8_WAIT_L(n) asm volatile("s_waitcnt lgkmcnt(" #n ")" ::: "memory")
; #define PG8_BAR __builtin_amdgcn_s_barrier()
; #define PG8_SCHED __builtin_amdgcn_sched_barrier(0)
; template <class Epi, class Sched, bool ALIGN_EPI = false, bool SP2 = false>
; __device__ __forceinline__ void gemm_phase(PG8_LAS unsigned char* lds, const Gemm g, const Sched& S, const Epi& E) {
;     ...
;             PG8_LDB(B0, 0, 0); PG8_LDB(B1, 0, 1); PG8_SCHED; PG8_LDA(At, 0, 0); PG8_STAGE(PG8_SA(1, 1), a1 + hstepA, voffA);
;             PG8_WAIT_V(8); PG8_WAIT_L(0); PG8_BAR; PG8_MMA(0, 0, At, B0); PG8_MMA(0, 1, At, B1); PG8_BAR; PG8_SCHED;
;             PG8_LDA(At, 0, 1); PG8_STAGE(PG8_SB(0, 0), b2, voffB); PG8_STAGE(PG8_SB(0, 1), b2 + hstepB, voffB); PG8_STAGE(PG8_SA(0, 0), a2, voffA);
;             PG8_WAIT_V(8); PG8_WAIT_L(0); PG8_BAR; PG8_MMA(1, 0, At, B0); PG8_MMA(1, 1, At, B1); PG8_BAR; PG8_SCHED;
.LBB0_157:
	v_add_u32_e32 v136, s2, v139
	ds_read_b128 v[186:189], v136
	ds_read_b128 v[190:193], v136 offset:1024
	ds_read_b128 v[194:197], v136 offset:2048
	ds_read_b128 v[198:201], v136 offset:3072
	v_add_u32_e32 v136, s3, v139
	ds_read_b128 v[202:205], v136
	ds_read_b128 v[206:209], v136 offset:1024
	ds_read_b128 v[210:213], v136 offset:2048
	ds_read_b128 v[214:217], v136 offset:3072
	s_add_u32 s38, s36, 0xfffc0080
	s_addc_u32 s39, s37, -1
	s_cmp_eq_u32 s45, 12
	s_cselect_b32 s41, s7, s39
	s_cselect_b32 s40, s29, s38
	s_cselect_b32 s39, s27, s44
	s_cselect_b32 s38, s42, s43
	v_lshl_add_u64 v[250:251], s[36:37], 0, v[178:179]
	s_add_i32 m0, s63, 0xc000
	ds_read_b128 v[218:221], v159
	ds_read_b128 v[222:225], v159 offset:1024
	ds_read_b128 v[226:229], v159 offset:2048
	ds_read_b128 v[230:233], v159 offset:3072
	ds_read_b128 v[234:237], v159 offset:4096
	ds_read_b128 v[238:241], v159 offset:5120
	ds_read_b128 v[242:245], v159 offset:6144
	ds_read_b128 v[246:249], v159 offset:7168
	global_load_lds_dwordx4 v[250:251], off
	v_lshl_add_u64 v[250:251], s[36:37], 0, v[180:181]
	s_add_i32 m0, s63, 0xe000
	s_nop 0
	global_load_lds_dwordx4 v[250:251], off
	s_waitcnt vmcnt(8)
	s_waitcnt lgkmcnt(0)
	s_barrier
	s_nop 0
	s_waitcnt lgkmcnt(0)
	v_mfma_f32_16x16x32_bf16 v[124:127], v[186:189], v[218:221], v[124:127]
	v_mfma_f32_16x16x32_bf16 v[120:123], v[194:197], v[218:221], v[120:123]
	v_mfma_f32_16x16x32_bf16 v[108:111], v[186:189], v[226:229], v[108:111]
	v_mfma_f32_16x16x32_bf16 v[104:107], v[194:197], v[226:229], v[104:107]
	v_mfma_f32_16x16x32_bf16 v[92:95], v[186:189], v[234:237], v[92:95]
	v_mfma_f32_16x16x32_bf16 v[88:91], v[194:197], v[234:237], v[88:91]
	v_mfma_f32_16x16x32_bf16 v[76:79], v[186:189], v[242:245], v[76:79]
	v_mfma_f32_16x16x32_bf16 v[72:75], v[194:197], v[242:245], v[72:75]
	v_mfma_f32_16x16x32_bf16 v[124:127], v[190:193], v[222:225], v[124:127]
	v_mfma_f32_16x16x32_bf16 v[120:123], v[198:201], v[222:225], v[120:123]
	v_mfma_f32_16x16x32_bf16 v[108:111], v[190:193], v[230:233], v[108:111]
	v_mfma_f32_16x16x32_bf16 v[104:107], v[198:201], v[230:233], v[104:107]
	v_mfma_f32_16x16x32_bf16 v[92:95], v[190:193], v[238:241], v[92:95]
	v_mfma_f32_16x16x32_bf16 v[88:91], v[198:201], v[238:241], v[88:91]
	v_mfma_f32_16x16x32_bf16 v[76:79], v[190:193], v[246:249], v[76:79]
	v_mfma_f32_16x16x32_bf16 v[72:75], v[198:201], v[246:249], v[72:75]
	v_mfma_f32_16x16x32_bf16 v[116:119], v[202:205], v[218:221], v[116:119]
	v_mfma_f32_16x16x32_bf16 v[112:115], v[210:213], v[218:221], v[112:115]
	v_mfma_f32_16x16x32_bf16 v[100:103], v[202:205], v[226:229], v[100:103]
	v_mfma_f32_16x16x32_bf16 v[96:99], v[210:213], v[226:229], v[96:99]
	v_mfma_f32_16x16x32_bf16 v[84:87], v[202:205], v[234:237], v[84:87]
	v_mfma_f32_16x16x32_bf16 v[80:83], v[210:213], v[234:237], v[80:83]
	v_mfma_f32_16x16x32_bf16 v[68:71], v[202:205], v[242:245], v[68:71]
	v_mfma_f32_16x16x32_bf16 v[64:67], v[210:213], v[242:245], v[64:67]
	v_mfma_f32_16x16x32_bf16 v[116:119], v[206:209], v[222:225], v[116:119]
	v_mfma_f32_16x16x32_bf16 v[112:115], v[214:217], v[222:225], v[112:115]
	v_mfma_f32_16x16x32_bf16 v[100:103], v[206:209], v[230:233], v[100:103]
	v_mfma_f32_16x16x32_bf16 v[96:99], v[214:217], v[230:233], v[96:99]
	v_mfma_f32_16x16x32_bf16 v[84:87], v[206:209], v[238:241], v[84:87]
	v_mfma_f32_16x16x32_bf16 v[80:83], v[214:217], v[238:241], v[80:83]
	v_mfma_f32_16x16x32_bf16 v[68:71], v[206:209], v[246:249], v[68:71]
	v_mfma_f32_16x16x32_bf16 v[64:67], v[214:217], v[246:249], v[64:67]
	s_nop 0
	s_barrier
	s_add_i32 s46, s2, s62
	v_lshl_add_u64 v[250:251], s[38:39], 0, v[130:131]
	s_mov_b32 m0, s46
	ds_read_b128 v[218:221], v159 offset:16384
	ds_read_b128 v[222:225], v159 offset:17408
	ds_read_b128 v[226:229], v159 offset:18432
	ds_read_b128 v[230:233], v159 offset:19456
	ds_read_b128 v[234:237], v159 offset:20480
	ds_read_b128 v[238:241], v159 offset:21504
	ds_read_b128 v[242:245], v159 offset:22528
	ds_read_b128 v[246:249], v159 offset:23552
	global_load_lds_dwordx4 v[250:251], off
	s_add_i32 m0, s46, 0x2000
	s_add_u32 s46, s38, 0x40000
	v_lshl_add_u64 v[252:253], s[38:39], 0, v[134:135]
	s_addc_u32 s47, s39, 0
	s_add_i32 s48, s3, s62
	global_load_lds_dwordx4 v[252:253], off
	v_lshl_add_u64 v[166:167], s[46:47], 0, v[130:131]
	s_mov_b32 m0, s48
	v_lshl_add_u64 v[168:169], s[40:41], 0, v[132:133]
	global_load_lds_dwordx4 v[166:167], off
	v_lshl_add_u64 v[166:167], s[46:47], 0, v[134:135]
	s_add_i32 m0, s48, 0x2000
	s_nop 0
	global_load_lds_dwordx4 v[166:167], off
	v_lshl_add_u64 v[166:167], s[40:41], 0, v[128:129]
	s_mov_b32 m0, s63
	s_nop 0
	global_load_lds_dwordx4 v[166:167], off
	s_mov_b32 m0, s64
	s_nop 0
	global_load_lds_dwordx4 v[168:169], off
	s_waitcnt vmcnt(8)
	s_waitcnt lgkmcnt(0)
	s_barrier
; #define PG8_STAGE(bufoff, gbase, voff) do { _Pragma("unroll") for (int _i = 0; _i < 2; ++_i) \
;         __builtin_amdgcn_global_load_lds((const unsigned*)((const char*)(gbase) + (voff)[_i]), (PG8_LAS unsigned*)(lds + (bufoff) + ldsw + _i * 8192), 16, 0, 0); } while (0)
; #define PG8_LDA(dst, b, h) do { _Pragma("unroll") for (int m = 0; m < 4; ++m) _Pragma("unroll") for (int k = 0; k < 2; ++k) dst[m][k] = *(const PG8_LAS bf16x8*)(lds + PG8_SA(b, h) + aoff + m * 2048 + k * 1024); } while (0)
; #define PG8_LDB(dst, b, h) do { _Pragma("unroll") for (int n = 0; n < 2; ++n) _Pragma("unroll") for (int k = 0; k < 2; ++k) dst[n][k] = *(const PG8_LAS bf16x8*)(lds + PG8_SB(b, h) + boff + n * 2048 + k * 1024); } while (0)
; #define PG8_MMA(ai, bj, At, Bt) do { __builtin_amdgcn_s_setprio(1); _Pragma("unroll") for (int m = 0; m < 4; ++m) _Pragma("unroll") for (int n = 0; n < 2; ++n) _Pragma("unroll") for (int k = 0; k < 2; ++k) \
;         acc[ai][bj][m][n] = __builtin_amdgcn_mfma_f32_16x16x32_bf16(Bt[n][k], At[m][k], acc[ai][bj][m][n], 0, 0, 0); __builtin_amdgcn_s_setprio(0); } while (0)
; #define PG8_WAIT_V(n) asm volatile("s_waitcnt vmcnt(" #n ")" ::: "memory")
; #define PG8_WAIT_L(n) asm volatile("s_waitcnt lgkmcnt(" #n ")" ::: "memory")
; #define PG8_BAR __builtin_amdgcn_s_barrier()
; #define PG8_SCHED __builtin_amdgcn_sched_barrier(0)
; template <class Epi, class Sched, bool ALIGN_EPI = false, bool SP2 = false>
; __device__ __forceinline__ void gemm_phase(PG8_LAS unsigned char* lds, const Gemm g, const Sched& S, const Epi& E) {
;     ...
;             PG8_WAIT_V(8); PG8_WAIT_L(0); PG8_BAR; PG8_MMA(1, 0, At, B0); PG8_MMA(1, 1, At, B1); PG8_BAR; PG8_SCHED;
;             PG8_LDB(B0, 1, 0); PG8_LDB(B1, 1, 1); PG8_SCHED; PG8_LDA(At, 1, 0); PG8_STAGE(PG8_SA(0, 1), a2 + hstepA, voffA);
;             PG8_WAIT_V(8); PG8_WAIT_L(0); PG8_BAR; PG8_MMA(0, 0, At, B0); PG8_MMA(0, 1, At, B1); PG8_BAR; PG8_SCHED;
	s_nop 0
	s_waitcnt lgkmcnt(0)
	v_mfma_f32_16x16x32_bf16 v[60:63], v[186:189], v[218:221], v[60:63]
	v_mfma_f32_16x16x32_bf16 v[56:59], v[194:197], v[218:221], v[56:59]
	v_mfma_f32_16x16x32_bf16 v[44:47], v[186:189], v[226:229], v[44:47]
	v_mfma_f32_16x16x32_bf16 v[40:43], v[194:197], v[226:229], v[40:43]
	v_mfma_f32_16x16x32_bf16 v[28:31], v[186:189], v[234:237], v[28:31]
	v_mfma_f32_16x16x32_bf16 v[24:27], v[194:197], v[234:237], v[24:27]
	v_mfma_f32_16x16x32_bf16 v[12:15], v[186:189], v[242:245], v[12:15]
	v_mfma_f32_16x16x32_bf16 v[8:11], v[194:197], v[242:245], v[8:11]
	v_mfma_f32_16x16x32_bf16 v[60:63], v[190:193], v[222:225], v[60:63]
	v_mfma_f32_16x16x32_bf16 v[56:59], v[198:201], v[222:225], v[56:59]
	v_mfma_f32_16x16x32_bf16 v[44:47], v[190:193], v[230:233], v[44:47]
	v_mfma_f32_16x16x32_bf16 v[40:43], v[198:201], v[230:233], v[40:43]
	v_mfma_f32_16x16x32_bf16 v[28:31], v[190:193], v[238:241], v[28:31]
	v_mfma_f32_16x16x32_bf16 v[24:27], v[198:201], v[238:241], v[24:27]
	v_mfma_f32_16x16x32_bf16 v[12:15], v[190:193], v[246:249], v[12:15]
	v_mfma_f32_16x16x32_bf16 v[8:11], v[198:201], v[246:249], v[8:11]
	v_mfma_f32_16x16x32_bf16 v[52:55], v[202:205], v[218:221], v[52:55]
	v_mfma_f32_16x16x32_bf16 v[48:51], v[210:213], v[218:221], v[48:51]
	v_mfma_f32_16x16x32_bf16 v[36:39], v[202:205], v[226:229], v[36:39]
	v_mfma_f32_16x16x32_bf16 v[32:35], v[210:213], v[226:229], v[32:35]
	v_mfma_f32_16x16x32_bf16 v[20:23], v[202:205], v[234:237], v[20:23]
	v_mfma_f32_16x16x32_bf16 v[16:19], v[210:213], v[234:237], v[16:19]
	v_mfma_f32_16x16x32_bf16 v[4:7], v[202:205], v[242:245], v[4:7]
	v_mfma_f32_16x16x32_bf16 v[0:3], v[210:213], v[242:245], v[0:3]
	v_mfma_f32_16x16x32_bf16 v[52:55], v[206:209], v[222:225], v[52:55]
	v_mfma_f32_16x16x32_bf16 v[48:51], v[214:217], v[222:225], v[48:51]
	v_mfma_f32_16x16x32_bf16 v[36:39], v[206:209], v[230:233], v[36:39]
	v_mfma_f32_16x16x32_bf16 v[32:35], v[214:217], v[230:233], v[32:35]
	v_mfma_f32_16x16x32_bf16 v[20:23], v[206:209], v[238:241], v[20:23]
	v_mfma_f32_16x16x32_bf16 v[16:19], v[214:217], v[238:241], v[16:19]
	v_mfma_f32_16x16x32_bf16 v[4:7], v[206:209], v[246:249], v[4:7]
	v_mfma_f32_16x16x32_bf16 v[0:3], v[214:217], v[246:249], v[0:3]
	s_nop 0
	s_barrier
	s_add_i32 s46, 0, 0x18000
	v_add_u32_e32 v136, s46, v139
	s_add_i32 s47, 0, 0x1c000
	ds_read_b128 v[186:189], v136
	ds_read_b128 v[190:193], v136 offset:1024
	ds_read_b128 v[194:197], v136 offset:2048
	ds_read_b128 v[198:201], v136 offset:3072
	v_add_u32_e32 v136, s47, v139
	ds_read_b128 v[202:205], v136
	ds_read_b128 v[206:209], v136 offset:1024
	ds_read_b128 v[210:213], v136 offset:2048
	ds_read_b128 v[214:217], v136 offset:3072
	s_add_u32 s40, s40, 0x40000
	s_addc_u32 s41, s41, 0
	s_mov_b32 m0, s65
	v_lshl_add_u64 v[170:171], s[40:41], 0, v[128:129]
	ds_read_b128 v[218:221], v159 offset:32768
	ds_read_b128 v[222:225], v159 offset:33792
	ds_read_b128 v[226:229], v159 offset:34816
	ds_read_b128 v[230:233], v159 offset:35840
	ds_read_b128 v[234:237], v159 offset:36864
	ds_read_b128 v[238:241], v159 offset:37888
	ds_read_b128 v[242:245], v159 offset:38912
	ds_read_b128 v[246:249], v159 offset:39936
	global_load_lds_dwordx4 v[170:171], off
	v_lshl_add_u64 v[170:171], s[40:41], 0, v[132:133]
	s_mov_b32 m0, s66
	s_nop 0
	global_load_lds_dwordx4 v[170:171], off
	s_waitcnt vmcnt(8)
	s_waitcnt lgkmcnt(0)
	s_barrier
	s_nop 0
	s_waitcnt lgkmcnt(0)
	v_mfma_f32_16x16x32_bf16 v[124:127], v[186:189], v[218:221], v[124:127]
	v_mfma_f32_16x16x32_bf16 v[120:123], v[194:197], v[218:221], v[120:123]
	v_mfma_f32_16x16x32_bf16 v[108:111], v[186:189], v[226:229], v[108:111]
	v_mfma_f32_16x16x32_bf16 v[104:107], v[194:197], v[226:229], v[104:107]
	v_mfma_f32_16x16x32_bf16 v[92:95], v[186:189], v[234:237], v[92:95]
	v_mfma_f32_16x16x32_bf16 v[88:91], v[194:197], v[234:237], v[88:91]
	v_mfma_f32_16x16x32_bf16 v[76:79], v[186:189], v[242:245], v[76:79]
	v_mfma_f32_16x16x32_bf16 v[72:75], v[194:197], v[242:245], v[72:75]
	v_mfma_f32_16x16x32_bf16 v[124:127], v[190:193], v[222:225], v[124:127]
	v_mfma_f32_16x16x32_bf16 v[120:123], v[198:201], v[222:225], v[120:123]
	v_mfma_f32_16x16x32_bf16 v[108:111], v[190:193], v[230:233], v[108:111]
	v_mfma_f32_16x16x32_bf16 v[104:107], v[198:201], v[230:233], v[104:107]
	v_mfma_f32_16x16x32_bf16 v[92:95], v[190:193], v[238:241], v[92:95]
	v_mfma_f32_16x16x32_bf16 v[88:91], v[198:201], v[238:241], v[88:91]
	v_mfma_f32_16x16x32_bf16 v[76:79], v[190:193], v[246:249], v[76:79]
	v_mfma_f32_16x16x32_bf16 v[72:75], v[198:201], v[246:249], v[72:75]
	v_mfma_f32_16x16x32_bf16 v[116:119], v[202:205], v[218:221], v[116:119]
	v_mfma_f32_16x16x32_bf16 v[112:115], v[210:213], v[218:221], v[112:115]
	v_mfma_f32_16x16x32_bf16 v[100:103], v[202:205], v[226:229], v[100:103]
	v_mfma_f32_16x16x32_bf16 v[96:99], v[210:213], v[226:229], v[96:99]
	v_mfma_f32_16x16x32_bf16 v[84:87], v[202:205], v[234:237], v[84:87]
	v_mfma_f32_16x16x32_bf16 v[80:83], v[210:213], v[234:237], v[80:83]
	v_mfma_f32_16x16x32_bf16 v[68:71], v[202:205], v[242:245], v[68:71]
	v_mfma_f32_16x16x32_bf16 v[64:67], v[210:213], v[242:245], v[64:67]
	v_mfma_f32_16x16x32_bf16 v[116:119], v[206:209], v[222:225], v[116:119]
	v_mfma_f32_16x16x32_bf16 v[112:115], v[214:217], v[222:225], v[112:115]
	v_mfma_f32_16x16x32_bf16 v[100:103], v[206:209], v[230:233], v[100:103]
	v_mfma_f32_16x16x32_bf16 v[96:99], v[214:217], v[230:233], v[96:99]
	v_mfma_f32_16x16x32_bf16 v[84:87], v[206:209], v[238:241], v[84:87]
	v_mfma_f32_16x16x32_bf16 v[80:83], v[214:217], v[238:241], v[80:83]
	v_mfma_f32_16x16x32_bf16 v[68:71], v[206:209], v[246:249], v[68:71]
	v_mfma_f32_16x16x32_bf16 v[64:67], v[214:217], v[246:249], v[64:67]
	s_nop 0
	s_barrier
; #define PG8_STAGE(bufoff, gbase, voff) do { _Pragma("unroll") for (int _i = 0; _i < 2; ++_i) \
;         __builtin_amdgcn_global_load_lds((const unsigned*)((const char*)(gbase) + (voff)[_i]), (PG8_LAS unsigned*)(lds + (bufoff) + ldsw + _i * 8192), 16, 0, 0); } while (0)
; #define PG8_LDA(dst, b, h) do { _Pragma("unroll") for (int m = 0; m < 4; ++m) _Pragma("unroll") for (int k = 0; k < 2; ++k) dst[m][k] = *(const PG8_LAS bf16x8*)(lds + PG8_SA(b, h) + aoff + m * 2048 + k * 1024); } while (0)
; #define PG8_MMA(ai, bj, At, Bt) do { __builtin_amdgcn_s_setprio(1); _Pragma("unroll") for (int m = 0; m < 4; ++m) _Pragma("unroll") for (int n = 0; n < 2; ++n) _Pragma("unroll") for (int k = 0; k < 2; ++k) \
;         acc[ai][bj][m][n] = __builtin_amdgcn_mfma_f32_16x16x32_bf16(Bt[n][k], At[m][k], acc[ai][bj][m][n], 0, 0, 0); __builtin_amdgcn_s_setprio(0); } while (0)
; #define PG8_WAIT_V(n) asm volatile("s_waitcnt vmcnt(" #n ")" ::: "memory")
; #define PG8_WAIT_L(n) asm volatile("s_waitcnt lgkmcnt(" #n ")" ::: "memory")
; #define PG8_BAR __builtin_amdgcn_s_barrier()
; #define PG8_SCHED __builtin_amdgcn_sched_barrier(0)
; template <class Epi, class Sched, bool ALIGN_EPI = false, bool SP2 = false>
; __device__ __forceinline__ void gemm_phase(PG8_LAS unsigned char* lds, const Gemm g, const Sched& S, const Epi& E) {
;     ...
;         for (int t = 0; t < nt; t += 2) {
;             const bool last = (t == nt - 2);
;             const char* a1 = cA + (size_t)(t + 1) * kstep;
;             const char* a2 = last ? nA : cA + (size_t)(t + 2) * kstep; const char* b2 = last ? nB : cB + (size_t)(t + 2) * kstep;
;             const char* a3 = a2 + kstep; const char* b3 = b2 + kstep;
;             if (last && has_next) S.a_ready(nxt);
;     ...
;             PG8_LDA(At, 1, 1); PG8_STAGE(PG8_SB(1, 0), b3, voffB); PG8_STAGE(PG8_SB(1, 1), b3 + hstepB, voffB); PG8_STAGE(PG8_SA(1, 0), a3, voffA);
;             PG8_WAIT_V(8); PG8_WAIT_L(0); PG8_BAR; PG8_MMA(1, 0, At, B0); PG8_MMA(1, 1, At, B1); PG8_BAR; PG8_SCHED;
	s_add_i32 s40, s46, s62
	v_lshl_add_u64 v[170:171], v[250:251], 0, s[22:23]
	s_mov_b32 m0, s40
	ds_read_b128 v[218:221], v159 offset:49152
	ds_read_b128 v[222:225], v159 offset:50176
	ds_read_b128 v[226:229], v159 offset:51200
	ds_read_b128 v[230:233], v159 offset:52224
	ds_read_b128 v[234:237], v159 offset:53248
	ds_read_b128 v[238:241], v159 offset:54272
	ds_read_b128 v[242:245], v159 offset:55296
	ds_read_b128 v[246:249], v159 offset:56320
	global_load_lds_dwordx4 v[170:171], off
	s_add_i32 m0, s40, 0x2000
	s_add_u32 s38, s38, 0x40080
	v_lshl_add_u64 v[170:171], v[252:253], 0, s[22:23]
	s_addc_u32 s39, s39, 0
	s_add_i32 s40, s47, s62
	global_load_lds_dwordx4 v[170:171], off
	v_lshl_add_u64 v[170:171], s[38:39], 0, v[130:131]
	s_mov_b32 m0, s40
	v_lshl_add_u64 v[166:167], v[166:167], 0, s[22:23]
	global_load_lds_dwordx4 v[170:171], off
	v_lshl_add_u64 v[170:171], s[38:39], 0, v[134:135]
	s_add_i32 m0, s40, 0x2000
	s_nop 0
	global_load_lds_dwordx4 v[170:171], off
	s_mov_b32 m0, s93
	s_nop 0
	global_load_lds_dwordx4 v[166:167], off
	v_lshl_add_u64 v[166:167], v[168:169], 0, s[22:23]
	s_mov_b32 m0, s96
	s_nop 0
	global_load_lds_dwordx4 v[166:167], off
	s_waitcnt vmcnt(8)
	s_waitcnt lgkmcnt(0)
	s_barrier
	s_nop 0
	s_waitcnt lgkmcnt(0)
	v_mfma_f32_16x16x32_bf16 v[60:63], v[186:189], v[218:221], v[60:63]
	v_mfma_f32_16x16x32_bf16 v[56:59], v[194:197], v[218:221], v[56:59]
	v_mfma_f32_16x16x32_bf16 v[44:47], v[186:189], v[226:229], v[44:47]
	v_mfma_f32_16x16x32_bf16 v[40:43], v[194:197], v[226:229], v[40:43]
	v_mfma_f32_16x16x32_bf16 v[28:31], v[186:189], v[234:237], v[28:31]
	v_mfma_f32_16x16x32_bf16 v[24:27], v[194:197], v[234:237], v[24:27]
	v_mfma_f32_16x16x32_bf16 v[12:15], v[186:189], v[242:245], v[12:15]
	v_mfma_f32_16x16x32_bf16 v[8:11], v[194:197], v[242:245], v[8:11]
	v_mfma_f32_16x16x32_bf16 v[60:63], v[190:193], v[222:225], v[60:63]
	v_mfma_f32_16x16x32_bf16 v[56:59], v[198:201], v[222:225], v[56:59]
	v_mfma_f32_16x16x32_bf16 v[44:47], v[190:193], v[230:233], v[44:47]
	v_mfma_f32_16x16x32_bf16 v[40:43], v[198:201], v[230:233], v[40:43]
	v_mfma_f32_16x16x32_bf16 v[28:31], v[190:193], v[238:241], v[28:31]
	v_mfma_f32_16x16x32_bf16 v[24:27], v[198:201], v[238:241], v[24:27]
	v_mfma_f32_16x16x32_bf16 v[12:15], v[190:193], v[246:249], v[12:15]
	v_mfma_f32_16x16x32_bf16 v[8:11], v[198:201], v[246:249], v[8:11]
	v_mfma_f32_16x16x32_bf16 v[52:55], v[202:205], v[218:221], v[52:55]
	v_mfma_f32_16x16x32_bf16 v[48:51], v[210:213], v[218:221], v[48:51]
	v_mfma_f32_16x16x32_bf16 v[36:39], v[202:205], v[226:229], v[36:39]
	v_mfma_f32_16x16x32_bf16 v[32:35], v[210:213], v[226:229], v[32:35]
	v_mfma_f32_16x16x32_bf16 v[20:23], v[202:205], v[234:237], v[20:23]
	v_mfma_f32_16x16x32_bf16 v[16:19], v[210:213], v[234:237], v[16:19]
	v_mfma_f32_16x16x32_bf16 v[4:7], v[202:205], v[242:245], v[4:7]
	v_mfma_f32_16x16x32_bf16 v[0:3], v[210:213], v[242:245], v[0:3]
	v_mfma_f32_16x16x32_bf16 v[52:55], v[206:209], v[222:225], v[52:55]
	v_mfma_f32_16x16x32_bf16 v[48:51], v[214:217], v[222:225], v[48:51]
	v_mfma_f32_16x16x32_bf16 v[36:39], v[206:209], v[230:233], v[36:39]
	v_mfma_f32_16x16x32_bf16 v[32:35], v[214:217], v[230:233], v[32:35]
	v_mfma_f32_16x16x32_bf16 v[20:23], v[206:209], v[238:241], v[20:23]
	v_mfma_f32_16x16x32_bf16 v[16:19], v[214:217], v[238:241], v[16:19]
	v_mfma_f32_16x16x32_bf16 v[4:7], v[206:209], v[246:249], v[4:7]
	v_mfma_f32_16x16x32_bf16 v[0:3], v[214:217], v[246:249], v[0:3]
	s_nop 0
	s_barrier
	s_add_i32 s45, s45, 2
	s_add_u32 s36, s36, 0x100
	s_addc_u32 s37, s37, 0
	s_add_u32 s43, s43, 0x100
	s_addc_u32 s44, s44, 0
	s_cmp_gt_u32 s45, 13
	s_cbranch_scc0 .LBB0_157
	s_and_b64 vcc, exec, s[24:25]
	s_cbranch_vccz .LBB0_160
	s_barrier

; #define PG8_STAGE(bufoff, gbase, voff) do { _Pragma("unroll") for (int _i = 0; _i < 2; ++_i) \
;         __builtin_amdgcn_global_load_lds((const unsigned*)((const char*)(gbase) + (voff)[_i]), (PG8_LAS unsigned*)(lds + (bufoff) + ldsw + _i * 8192), 16, 0, 0); } while (0)
; #define PG8_LDA(dst, b, h) do { _Pragma("unroll") for (int m = 0; m < 4; ++m) _Pragma("unroll") for (int k = 0; k < 2; ++k) dst[m][k] = *(const PG8_LAS bf16x8*)(lds + PG8_SA(b, h) + aoff + m * 2048 + k * 1024); } while (0)
; #define PG8_LDB(dst, b, h) do { _Pragma("unroll") for (int n = 0; n < 2; ++n) _Pragma("unroll") for (int k = 0; k < 2; ++k) dst[n][k] = *(const PG8_LAS bf16x8*)(lds + PG8_SB(b, h) + boff + n * 2048 + k * 1024); } while (0)
; #define PG8_MMA(ai, bj, At, Bt) do { __builtin_amdgcn_s_setprio(1); _Pragma("unroll") for (int m = 0; m < 4; ++m) _Pragma("unroll") for (int n = 0; n < 2; ++n) _Pragma("unroll") for (int k = 0; k < 2; ++k) \
;         acc[ai][bj][m][n] = __builtin_amdgcn_mfma_f32_16x16x32_bf16(Bt[n][k], At[m][k], acc[ai][bj][m][n], 0, 0, 0); __builtin_amdgcn_s_setprio(0); } while (0)
; #define PG8_WAIT_V(n) asm volatile("s_waitcnt vmcnt(" #n ")" ::: "memory")
; #define PG8_BAR __builtin_amdgcn_s_barrier()
; template <class Epi, class Sched, bool ALIGN_EPI = false, bool SP2 = false>
; __device__ __forceinline__ void gemm_phase(PG8_LAS unsigned char* lds, const Gemm g, const Sched& S, const Epi& E) {
;     ...
;         for (int t = 0; t < nt; t += 2) {
;             const bool last = (t == nt - 2);
;             const char* a1 = cA + (size_t)(t + 1) * kstep;
;             const char* a2 = last ? nA : cA + (size_t)(t + 2) * kstep; const char* b2 = last ? nB : cB + (size_t)(t + 2) * kstep;
;             const char* a3 = a2 + kstep; const char* b3 = b2 + kstep;
;             if (last && has_next) S.a_ready(nxt);
;             if constexpr (SP2) {
;             PG8_LDB(B0, 0, 0); PG8_LDB(B1, 0, 1); PG8_SCHED; PG8_LDA(At, 0, 0); PG8_STAGE(PG8_SA(1, 1), a1 + hstepA, voffA);
;             PG8_WAIT_V(8); PG8_WAIT_L(0); PG8_BAR; PG8_MMA(0, 0, At, B0); PG8_MMA(0, 1, At, B1); PG8_BAR; PG8_SCHED;
;             PG8_LDA(At, 0, 1); PG8_STAGE(PG8_SB(0, 0), b2, voffB); PG8_STAGE(PG8_SB(0, 1), b2 + hstepB, voffB); PG8_STAGE(PG8_SA(0, 0), a2, voffA);
;             PG8_WAIT_V(8); PG8_WAIT_L(0); PG8_BAR; PG8_MMA(1, 0, At, B0); PG8_MMA(1, 1, At, B1); PG8_BAR; PG8_SCHED;
.LBB0_470:
	ds_read_b128 v[158:161], v155
	ds_read_b128 v[162:165], v155 offset:1024
	ds_read_b128 v[166:169], v155 offset:2048
	ds_read_b128 v[170:173], v155 offset:3072
	ds_read_b128 v[174:177], v156
	ds_read_b128 v[178:181], v156 offset:1024
	ds_read_b128 v[186:189], v156 offset:2048
	ds_read_b128 v[190:193], v156 offset:3072
	s_add_u32 s12, s0, 0xfffc0080
	s_addc_u32 s13, s1, -1
	s_cmp_eq_u32 s44, 4
	s_cselect_b32 s17, s38, s13
	s_cselect_b32 s16, s39, s12
	s_cselect_b32 s13, s40, s43
	s_cselect_b32 s12, s41, s42
	v_lshl_add_u64 v[182:183], s[0:1], 0, v[140:141]
	s_add_i32 m0, s22, 0xc000
	ds_read_b128 v[194:197], v157
	ds_read_b128 v[198:201], v157 offset:1024
	ds_read_b128 v[202:205], v157 offset:2048
	ds_read_b128 v[206:209], v157 offset:3072
	ds_read_b128 v[210:213], v157 offset:4096
	ds_read_b128 v[214:217], v157 offset:5120
	ds_read_b128 v[218:221], v157 offset:6144
	ds_read_b128 v[222:225], v157 offset:7168
	global_load_lds_dwordx4 v[182:183], off
	v_lshl_add_u64 v[182:183], s[0:1], 0, v[142:143]
	s_add_i32 m0, s22, 0xe000
	s_nop 0
	global_load_lds_dwordx4 v[182:183], off
	s_waitcnt vmcnt(8)
	s_waitcnt lgkmcnt(0)
	s_barrier
	s_nop 0
	s_waitcnt lgkmcnt(0)
	v_mfma_f32_16x16x32_bf16 v[124:127], v[158:161], v[194:197], v[124:127]
	v_mfma_f32_16x16x32_bf16 v[120:123], v[166:169], v[194:197], v[120:123]
	v_mfma_f32_16x16x32_bf16 v[116:119], v[158:161], v[202:205], v[116:119]
	v_mfma_f32_16x16x32_bf16 v[112:115], v[166:169], v[202:205], v[112:115]
	v_mfma_f32_16x16x32_bf16 v[108:111], v[158:161], v[210:213], v[108:111]
	v_mfma_f32_16x16x32_bf16 v[100:103], v[166:169], v[210:213], v[100:103]
	v_mfma_f32_16x16x32_bf16 v[92:95], v[158:161], v[218:221], v[92:95]
	v_mfma_f32_16x16x32_bf16 v[84:87], v[166:169], v[218:221], v[84:87]
	v_mfma_f32_16x16x32_bf16 v[124:127], v[162:165], v[198:201], v[124:127]
	v_mfma_f32_16x16x32_bf16 v[120:123], v[170:173], v[198:201], v[120:123]
	v_mfma_f32_16x16x32_bf16 v[116:119], v[162:165], v[206:209], v[116:119]
	v_mfma_f32_16x16x32_bf16 v[112:115], v[170:173], v[206:209], v[112:115]
	v_mfma_f32_16x16x32_bf16 v[108:111], v[162:165], v[214:217], v[108:111]
	v_mfma_f32_16x16x32_bf16 v[100:103], v[170:173], v[214:217], v[100:103]
	v_mfma_f32_16x16x32_bf16 v[92:95], v[162:165], v[222:225], v[92:95]
	v_mfma_f32_16x16x32_bf16 v[84:87], v[170:173], v[222:225], v[84:87]
	v_mfma_f32_16x16x32_bf16 v[104:107], v[174:177], v[194:197], v[104:107]
	v_mfma_f32_16x16x32_bf16 v[96:99], v[186:189], v[194:197], v[96:99]
	v_mfma_f32_16x16x32_bf16 v[88:91], v[174:177], v[202:205], v[88:91]
	v_mfma_f32_16x16x32_bf16 v[80:83], v[186:189], v[202:205], v[80:83]
	v_mfma_f32_16x16x32_bf16 v[76:79], v[174:177], v[210:213], v[76:79]
	v_mfma_f32_16x16x32_bf16 v[72:75], v[186:189], v[210:213], v[72:75]
	v_mfma_f32_16x16x32_bf16 v[68:71], v[174:177], v[218:221], v[68:71]
	v_mfma_f32_16x16x32_bf16 v[64:67], v[186:189], v[218:221], v[64:67]
	v_mfma_f32_16x16x32_bf16 v[104:107], v[178:181], v[198:201], v[104:107]
	v_mfma_f32_16x16x32_bf16 v[96:99], v[190:193], v[198:201], v[96:99]
	v_mfma_f32_16x16x32_bf16 v[88:91], v[178:181], v[206:209], v[88:91]
	v_mfma_f32_16x16x32_bf16 v[80:83], v[190:193], v[206:209], v[80:83]
	v_mfma_f32_16x16x32_bf16 v[76:79], v[178:181], v[214:217], v[76:79]
	v_mfma_f32_16x16x32_bf16 v[72:75], v[190:193], v[214:217], v[72:75]
	v_mfma_f32_16x16x32_bf16 v[68:71], v[178:181], v[222:225], v[68:71]
	v_mfma_f32_16x16x32_bf16 v[64:67], v[190:193], v[222:225], v[64:67]
	s_nop 0
	s_barrier
	s_add_i32 s45, s33, s15
	v_lshl_add_u64 v[182:183], s[12:13], 0, v[132:133]
	s_mov_b32 m0, s45
	ds_read_b128 v[194:197], v157 offset:16384
	ds_read_b128 v[198:201], v157 offset:17408
	ds_read_b128 v[202:205], v157 offset:18432
	ds_read_b128 v[206:209], v157 offset:19456
	ds_read_b128 v[210:213], v157 offset:20480
	ds_read_b128 v[214:217], v157 offset:21504
	ds_read_b128 v[218:221], v157 offset:22528
	ds_read_b128 v[222:225], v157 offset:23552
	global_load_lds_dwordx4 v[182:183], off
	s_add_i32 m0, s45, 0x2000
	s_add_u32 s46, s12, 0x80000
	v_lshl_add_u64 v[226:227], s[12:13], 0, v[128:129]
	s_addc_u32 s47, s13, 0
	s_add_i32 s45, s34, s15
	global_load_lds_dwordx4 v[226:227], off
	v_lshl_add_u64 v[228:229], s[46:47], 0, v[132:133]
	s_mov_b32 m0, s45
	v_lshl_add_u64 v[230:231], s[16:17], 0, v[130:131]
	global_load_lds_dwordx4 v[228:229], off
	v_lshl_add_u64 v[228:229], s[46:47], 0, v[128:129]
	s_add_i32 m0, s45, 0x2000
	s_nop 0
	global_load_lds_dwordx4 v[228:229], off
	v_lshl_add_u64 v[228:229], s[16:17], 0, v[134:135]
	s_mov_b32 m0, s22
	s_nop 0
	global_load_lds_dwordx4 v[228:229], off
	s_mov_b32 m0, s25
	s_nop 0
	global_load_lds_dwordx4 v[230:231], off
	s_waitcnt vmcnt(8)
	s_waitcnt lgkmcnt(0)
	s_barrier
; #define PG8_STAGE(bufoff, gbase, voff) do { _Pragma("unroll") for (int _i = 0; _i < 2; ++_i) \
;         __builtin_amdgcn_global_load_lds((const unsigned*)((const char*)(gbase) + (voff)[_i]), (PG8_LAS unsigned*)(lds + (bufoff) + ldsw + _i * 8192), 16, 0, 0); } while (0)
; #define PG8_LDA(dst, b, h) do { _Pragma("unroll") for (int m = 0; m < 4; ++m) _Pragma("unroll") for (int k = 0; k < 2; ++k) dst[m][k] = *(const PG8_LAS bf16x8*)(lds + PG8_SA(b, h) + aoff + m * 2048 + k * 1024); } while (0)
; #define PG8_LDB(dst, b, h) do { _Pragma("unroll") for (int n = 0; n < 2; ++n) _Pragma("unroll") for (int k = 0; k < 2; ++k) dst[n][k] = *(const PG8_LAS bf16x8*)(lds + PG8_SB(b, h) + boff + n * 2048 + k * 1024); } while (0)
; #define PG8_MMA(ai, bj, At, Bt) do { __builtin_amdgcn_s_setprio(1); _Pragma("unroll") for (int m = 0; m < 4; ++m) _Pragma("unroll") for (int n = 0; n < 2; ++n) _Pragma("unroll") for (int k = 0; k < 2; ++k) \
;         acc[ai][bj][m][n] = __builtin_amdgcn_mfma_f32_16x16x32_bf16(Bt[n][k], At[m][k], acc[ai][bj][m][n], 0, 0, 0); __builtin_amdgcn_s_setprio(0); } while (0)
; #define PG8_WAIT_V(n) asm volatile("s_waitcnt vmcnt(" #n ")" ::: "memory")
; #define PG8_WAIT_L(n) asm volatile("s_waitcnt lgkmcnt(" #n ")" ::: "memory")
; #define PG8_BAR __builtin_amdgcn_s_barrier()
; #define PG8_SCHED __builtin_amdgcn_sched_barrier(0)
; template <class Epi, class Sched, bool ALIGN_EPI = false, bool SP2 = false>
; __device__ __forceinline__ void gemm_phase(PG8_LAS unsigned char* lds, const Gemm g, const Sched& S, const Epi& E) {
;     ...
;             PG8_WAIT_V(8); PG8_WAIT_L(0); PG8_BAR; PG8_MMA(1, 0, At, B0); PG8_MMA(1, 1, At, B1); PG8_BAR; PG8_SCHED;
;             PG8_LDB(B0, 1, 0); PG8_LDB(B1, 1, 1); PG8_SCHED; PG8_LDA(At, 1, 0); PG8_STAGE(PG8_SA(0, 1), a2 + hstepA, voffA);
;             PG8_WAIT_V(8); PG8_WAIT_L(0); PG8_BAR; PG8_MMA(0, 0, At, B0); PG8_MMA(0, 1, At, B1); PG8_BAR; PG8_SCHED;
	s_nop 0
	s_waitcnt lgkmcnt(0)
	v_mfma_f32_16x16x32_bf16 v[60:63], v[158:161], v[194:197], v[60:63]
	v_mfma_f32_16x16x32_bf16 v[56:59], v[166:169], v[194:197], v[56:59]
	v_mfma_f32_16x16x32_bf16 v[52:55], v[158:161], v[202:205], v[52:55]
	v_mfma_f32_16x16x32_bf16 v[48:51], v[166:169], v[202:205], v[48:51]
	v_mfma_f32_16x16x32_bf16 v[44:47], v[158:161], v[210:213], v[44:47]
	v_mfma_f32_16x16x32_bf16 v[36:39], v[166:169], v[210:213], v[36:39]
	v_mfma_f32_16x16x32_bf16 v[28:31], v[158:161], v[218:221], v[28:31]
	v_mfma_f32_16x16x32_bf16 v[20:23], v[166:169], v[218:221], v[20:23]
	v_mfma_f32_16x16x32_bf16 v[60:63], v[162:165], v[198:201], v[60:63]
	v_mfma_f32_16x16x32_bf16 v[56:59], v[170:173], v[198:201], v[56:59]
	v_mfma_f32_16x16x32_bf16 v[52:55], v[162:165], v[206:209], v[52:55]
	v_mfma_f32_16x16x32_bf16 v[48:51], v[170:173], v[206:209], v[48:51]
	v_mfma_f32_16x16x32_bf16 v[44:47], v[162:165], v[214:217], v[44:47]
	v_mfma_f32_16x16x32_bf16 v[36:39], v[170:173], v[214:217], v[36:39]
	v_mfma_f32_16x16x32_bf16 v[28:31], v[162:165], v[222:225], v[28:31]
	v_mfma_f32_16x16x32_bf16 v[20:23], v[170:173], v[222:225], v[20:23]
	v_mfma_f32_16x16x32_bf16 v[40:43], v[174:177], v[194:197], v[40:43]
	v_mfma_f32_16x16x32_bf16 v[32:35], v[186:189], v[194:197], v[32:35]
	v_mfma_f32_16x16x32_bf16 v[24:27], v[174:177], v[202:205], v[24:27]
	v_mfma_f32_16x16x32_bf16 v[16:19], v[186:189], v[202:205], v[16:19]
	v_mfma_f32_16x16x32_bf16 v[12:15], v[174:177], v[210:213], v[12:15]
	v_mfma_f32_16x16x32_bf16 v[8:11], v[186:189], v[210:213], v[8:11]
	v_mfma_f32_16x16x32_bf16 v[4:7], v[174:177], v[218:221], v[4:7]
	v_mfma_f32_16x16x32_bf16 v[0:3], v[186:189], v[218:221], v[0:3]
	v_mfma_f32_16x16x32_bf16 v[40:43], v[178:181], v[198:201], v[40:43]
	v_mfma_f32_16x16x32_bf16 v[32:35], v[190:193], v[198:201], v[32:35]
	v_mfma_f32_16x16x32_bf16 v[24:27], v[178:181], v[206:209], v[24:27]
	v_mfma_f32_16x16x32_bf16 v[16:19], v[190:193], v[206:209], v[16:19]
	v_mfma_f32_16x16x32_bf16 v[12:15], v[178:181], v[214:217], v[12:15]
	v_mfma_f32_16x16x32_bf16 v[8:11], v[190:193], v[214:217], v[8:11]
	v_mfma_f32_16x16x32_bf16 v[4:7], v[178:181], v[222:225], v[4:7]
	v_mfma_f32_16x16x32_bf16 v[0:3], v[190:193], v[222:225], v[0:3]
	s_nop 0
	s_barrier
	s_add_i32 s45, 0, 0x18000
	v_add_u32_e32 v136, s45, v150
	s_add_i32 s46, 0, 0x1c000
	ds_read_b128 v[158:161], v136
	ds_read_b128 v[162:165], v136 offset:1024
	ds_read_b128 v[166:169], v136 offset:2048
	ds_read_b128 v[170:173], v136 offset:3072
	v_add_u32_e32 v136, s46, v150
	ds_read_b128 v[174:177], v136
	ds_read_b128 v[178:181], v136 offset:1024
	ds_read_b128 v[186:189], v136 offset:2048
	ds_read_b128 v[190:193], v136 offset:3072
	s_add_u32 s16, s16, 0x40000
	s_addc_u32 s17, s17, 0
	s_mov_b32 m0, s26
	v_lshl_add_u64 v[232:233], s[16:17], 0, v[134:135]
	ds_read_b128 v[194:197], v157 offset:32768
	ds_read_b128 v[198:201], v157 offset:33792
	ds_read_b128 v[202:205], v157 offset:34816
	ds_read_b128 v[206:209], v157 offset:35840
	ds_read_b128 v[210:213], v157 offset:36864
	ds_read_b128 v[214:217], v157 offset:37888
	ds_read_b128 v[218:221], v157 offset:38912
	ds_read_b128 v[222:225], v157 offset:39936
	global_load_lds_dwordx4 v[232:233], off
	v_lshl_add_u64 v[232:233], s[16:17], 0, v[130:131]
	s_mov_b32 m0, s27
	s_nop 0
	global_load_lds_dwordx4 v[232:233], off
	s_waitcnt vmcnt(8)
	s_waitcnt lgkmcnt(0)
	s_barrier
	s_nop 0
	s_waitcnt lgkmcnt(0)
	v_mfma_f32_16x16x32_bf16 v[124:127], v[158:161], v[194:197], v[124:127]
	v_mfma_f32_16x16x32_bf16 v[120:123], v[166:169], v[194:197], v[120:123]
	v_mfma_f32_16x16x32_bf16 v[116:119], v[158:161], v[202:205], v[116:119]
	v_mfma_f32_16x16x32_bf16 v[112:115], v[166:169], v[202:205], v[112:115]
	v_mfma_f32_16x16x32_bf16 v[108:111], v[158:161], v[210:213], v[108:111]
	v_mfma_f32_16x16x32_bf16 v[100:103], v[166:169], v[210:213], v[100:103]
	v_mfma_f32_16x16x32_bf16 v[92:95], v[158:161], v[218:221], v[92:95]
	v_mfma_f32_16x16x32_bf16 v[84:87], v[166:169], v[218:221], v[84:87]
	v_mfma_f32_16x16x32_bf16 v[124:127], v[162:165], v[198:201], v[124:127]
	v_mfma_f32_16x16x32_bf16 v[120:123], v[170:173], v[198:201], v[120:123]
	v_mfma_f32_16x16x32_bf16 v[116:119], v[162:165], v[206:209], v[116:119]
	v_mfma_f32_16x16x32_bf16 v[112:115], v[170:173], v[206:209], v[112:115]
	v_mfma_f32_16x16x32_bf16 v[108:111], v[162:165], v[214:217], v[108:111]
	v_mfma_f32_16x16x32_bf16 v[100:103], v[170:173], v[214:217], v[100:103]
	v_mfma_f32_16x16x32_bf16 v[92:95], v[162:165], v[222:225], v[92:95]
	v_mfma_f32_16x16x32_bf16 v[84:87], v[170:173], v[222:225], v[84:87]
	v_mfma_f32_16x16x32_bf16 v[104:107], v[174:177], v[194:197], v[104:107]
	v_mfma_f32_16x16x32_bf16 v[96:99], v[186:189], v[194:197], v[96:99]
	v_mfma_f32_16x16x32_bf16 v[88:91], v[174:177], v[202:205], v[88:91]
	v_mfma_f32_16x16x32_bf16 v[80:83], v[186:189], v[202:205], v[80:83]
	v_mfma_f32_16x16x32_bf16 v[76:79], v[174:177], v[210:213], v[76:79]
	v_mfma_f32_16x16x32_bf16 v[72:75], v[186:189], v[210:213], v[72:75]
	v_mfma_f32_16x16x32_bf16 v[68:71], v[174:177], v[218:221], v[68:71]
	v_mfma_f32_16x16x32_bf16 v[64:67], v[186:189], v[218:221], v[64:67]
	v_mfma_f32_16x16x32_bf16 v[104:107], v[178:181], v[198:201], v[104:107]
	v_mfma_f32_16x16x32_bf16 v[96:99], v[190:193], v[198:201], v[96:99]
	v_mfma_f32_16x16x32_bf16 v[88:91], v[178:181], v[206:209], v[88:91]
	v_mfma_f32_16x16x32_bf16 v[80:83], v[190:193], v[206:209], v[80:83]
	v_mfma_f32_16x16x32_bf16 v[76:79], v[178:181], v[214:217], v[76:79]
	v_mfma_f32_16x16x32_bf16 v[72:75], v[190:193], v[214:217], v[72:75]
	v_mfma_f32_16x16x32_bf16 v[68:71], v[178:181], v[222:225], v[68:71]
	v_mfma_f32_16x16x32_bf16 v[64:67], v[190:193], v[222:225], v[64:67]
	s_nop 0
	s_barrier
; #define PG8_STAGE(bufoff, gbase, voff) do { _Pragma("unroll") for (int _i = 0; _i < 2; ++_i) \
;         __builtin_amdgcn_global_load_lds((const unsigned*)((const char*)(gbase) + (voff)[_i]), (PG8_LAS unsigned*)(lds + (bufoff) + ldsw + _i * 8192), 16, 0, 0); } while (0)
; #define PG8_LDA(dst, b, h) do { _Pragma("unroll") for (int m = 0; m < 4; ++m) _Pragma("unroll") for (int k = 0; k < 2; ++k) dst[m][k] = *(const PG8_LAS bf16x8*)(lds + PG8_SA(b, h) + aoff + m * 2048 + k * 1024); } while (0)
; #define PG8_MMA(ai, bj, At, Bt) do { __builtin_amdgcn_s_setprio(1); _Pragma("unroll") for (int m = 0; m < 4; ++m) _Pragma("unroll") for (int n = 0; n < 2; ++n) _Pragma("unroll") for (int k = 0; k < 2; ++k) \
;         acc[ai][bj][m][n] = __builtin_amdgcn_mfma_f32_16x16x32_bf16(Bt[n][k], At[m][k], acc[ai][bj][m][n], 0, 0, 0); __builtin_amdgcn_s_setprio(0); } while (0)
; #define PG8_WAIT_V(n) asm volatile("s_waitcnt vmcnt(" #n ")" ::: "memory")
; #define PG8_WAIT_L(n) asm volatile("s_waitcnt lgkmcnt(" #n ")" ::: "memory")
; #define PG8_BAR __builtin_amdgcn_s_barrier()
; #define PG8_SCHED __builtin_amdgcn_sched_barrier(0)
; template <class Epi, class Sched, bool ALIGN_EPI = false, bool SP2 = false>
; __device__ __forceinline__ void gemm_phase(PG8_LAS unsigned char* lds, const Gemm g, const Sched& S, const Epi& E) {
;     ...
;             PG8_LDA(At, 1, 1); PG8_STAGE(PG8_SB(1, 0), b3, voffB); PG8_STAGE(PG8_SB(1, 1), b3 + hstepB, voffB); PG8_STAGE(PG8_SA(1, 0), a3, voffA);
;             PG8_WAIT_V(8); PG8_WAIT_L(0); PG8_BAR; PG8_MMA(1, 0, At, B0); PG8_MMA(1, 1, At, B1); PG8_BAR; PG8_SCHED;
;     __device__ __forceinline__ void operator()(const f32x4 (&acc)[2][2][4][2], const pg8::Unit& u, int wr, int wc, int fr, int fq) const {
;         float* base = part + (size_t)(u.koff >> 10) * 8192 * 256;
; #pragma unroll
;         for (int ai = 0; ai < 2; ++ai)
; #pragma unroll
;             for (int m = 0; m < 4; ++m) {
;                 const int row = u.pm * 256 + ai * 128 + wr * 64 + m * 16 + fr;
; #pragma unroll
;                 for (int bj = 0; bj < 2; ++bj) {
;                     float* p = base + (size_t)row * 256 + 128 * bj + 32 * wc + 8 * fq;
;                     *(f32x4*)p = acc[ai][bj][m][0]; *(f32x4*)(p + 4) = acc[ai][bj][m][1];
;                 }
;             }
	s_add_i32 s16, s45, s15
	v_lshl_add_u64 v[182:183], v[182:183], 0, s[10:11]
	s_mov_b32 m0, s16
	ds_read_b128 v[194:197], v157 offset:49152
	ds_read_b128 v[198:201], v157 offset:50176
	ds_read_b128 v[202:205], v157 offset:51200
	ds_read_b128 v[206:209], v157 offset:52224
	ds_read_b128 v[210:213], v157 offset:53248
	ds_read_b128 v[214:217], v157 offset:54272
	ds_read_b128 v[218:221], v157 offset:55296
	ds_read_b128 v[222:225], v157 offset:56320
	global_load_lds_dwordx4 v[182:183], off
	s_add_i32 m0, s16, 0x2000
	s_add_u32 s12, s12, 0x80080
	v_lshl_add_u64 v[182:183], v[226:227], 0, s[10:11]
	s_addc_u32 s13, s13, 0
	s_add_i32 s16, s46, s15
	global_load_lds_dwordx4 v[182:183], off
	v_lshl_add_u64 v[182:183], s[12:13], 0, v[132:133]
	s_mov_b32 m0, s16
	s_nop 0
	global_load_lds_dwordx4 v[182:183], off
	v_lshl_add_u64 v[182:183], s[12:13], 0, v[128:129]
	s_add_i32 m0, s16, 0x2000
	s_nop 0
	global_load_lds_dwordx4 v[182:183], off
	v_lshl_add_u64 v[182:183], v[228:229], 0, s[10:11]
	s_mov_b32 m0, s30
	s_nop 0
	global_load_lds_dwordx4 v[182:183], off
	v_lshl_add_u64 v[182:183], v[230:231], 0, s[10:11]
	s_mov_b32 m0, s31
	s_nop 0
	global_load_lds_dwordx4 v[182:183], off
	s_waitcnt vmcnt(8)
	s_waitcnt lgkmcnt(0)
	s_barrier
	s_nop 0
	s_waitcnt lgkmcnt(0)
	v_mfma_f32_16x16x32_bf16 v[60:63], v[158:161], v[194:197], v[60:63]
	v_mfma_f32_16x16x32_bf16 v[56:59], v[166:169], v[194:197], v[56:59]
	v_mfma_f32_16x16x32_bf16 v[52:55], v[158:161], v[202:205], v[52:55]
	v_mfma_f32_16x16x32_bf16 v[48:51], v[166:169], v[202:205], v[48:51]
	v_mfma_f32_16x16x32_bf16 v[44:47], v[158:161], v[210:213], v[44:47]
	v_mfma_f32_16x16x32_bf16 v[36:39], v[166:169], v[210:213], v[36:39]
	v_mfma_f32_16x16x32_bf16 v[28:31], v[158:161], v[218:221], v[28:31]
	v_mfma_f32_16x16x32_bf16 v[20:23], v[166:169], v[218:221], v[20:23]
	v_mfma_f32_16x16x32_bf16 v[60:63], v[162:165], v[198:201], v[60:63]
	v_mfma_f32_16x16x32_bf16 v[56:59], v[170:173], v[198:201], v[56:59]
	v_mfma_f32_16x16x32_bf16 v[52:55], v[162:165], v[206:209], v[52:55]
	v_mfma_f32_16x16x32_bf16 v[48:51], v[170:173], v[206:209], v[48:51]
	v_mfma_f32_16x16x32_bf16 v[44:47], v[162:165], v[214:217], v[44:47]
	v_mfma_f32_16x16x32_bf16 v[36:39], v[170:173], v[214:217], v[36:39]
	v_mfma_f32_16x16x32_bf16 v[28:31], v[162:165], v[222:225], v[28:31]
	v_mfma_f32_16x16x32_bf16 v[20:23], v[170:173], v[222:225], v[20:23]
	v_mfma_f32_16x16x32_bf16 v[40:43], v[174:177], v[194:197], v[40:43]
	v_mfma_f32_16x16x32_bf16 v[32:35], v[186:189], v[194:197], v[32:35]
	v_mfma_f32_16x16x32_bf16 v[24:27], v[174:177], v[202:205], v[24:27]
	v_mfma_f32_16x16x32_bf16 v[16:19], v[186:189], v[202:205], v[16:19]
	v_mfma_f32_16x16x32_bf16 v[12:15], v[174:177], v[210:213], v[12:15]
	v_mfma_f32_16x16x32_bf16 v[8:11], v[186:189], v[210:213], v[8:11]
	v_mfma_f32_16x16x32_bf16 v[4:7], v[174:177], v[218:221], v[4:7]
	v_mfma_f32_16x16x32_bf16 v[0:3], v[186:189], v[218:221], v[0:3]
	v_mfma_f32_16x16x32_bf16 v[40:43], v[178:181], v[198:201], v[40:43]
	v_mfma_f32_16x16x32_bf16 v[32:35], v[190:193], v[198:201], v[32:35]
	v_mfma_f32_16x16x32_bf16 v[24:27], v[178:181], v[206:209], v[24:27]
	v_mfma_f32_16x16x32_bf16 v[16:19], v[190:193], v[206:209], v[16:19]
	v_mfma_f32_16x16x32_bf16 v[12:15], v[178:181], v[214:217], v[12:15]
	v_mfma_f32_16x16x32_bf16 v[8:11], v[190:193], v[214:217], v[8:11]
	v_mfma_f32_16x16x32_bf16 v[4:7], v[178:181], v[222:225], v[4:7]
	v_mfma_f32_16x16x32_bf16 v[0:3], v[190:193], v[222:225], v[0:3]
	s_nop 0
	s_barrier
	s_add_i32 s44, s44, 2
	s_add_u32 s0, s0, 0x100
	s_addc_u32 s1, s1, 0
	s_add_u32 s42, s42, 0x100
	s_addc_u32 s43, s43, 0
	s_cmp_gt_u32 s44, 5
	s_cbranch_scc0 .LBB0_470
	s_ashr_i32 s0, s24, 10
	s_ashr_i32 s1, s0, 31
	s_lshl_b64 s[0:1], s[0:1], 23
	v_lshl_add_u64 v[158:159], v[138:139], 0, s[0:1]
	s_lshl_b32 s0, s23, 8
	v_add_u32_e32 v136, s0, v148
	v_lshlrev_b64 v[160:161], 10, v[136:137]
	v_lshl_add_u64 v[160:161], v[158:159], 0, v[160:161]
	global_store_dwordx4 v[160:161], v[124:127], off
	global_store_dwordx4 v[160:161], v[120:123], off offset:16
	global_store_dwordx4 v[160:161], v[104:107], off offset:512
	global_store_dwordx4 v[160:161], v[96:99], off offset:528
	s_and_b64 vcc, exec, vcc
	s_mov_b32 s24, s35
	v_add_u32_e32 v96, s0, v152
	v_mov_b32_e32 v97, v137
	v_lshlrev_b64 v[96:97], 10, v[96:97]
	v_lshl_add_u64 v[96:97], v[158:159], 0, v[96:97]
	global_store_dwordx4 v[96:97], v[116:119], off
	global_store_dwordx4 v[96:97], v[112:115], off offset:16
	global_store_dwordx4 v[96:97], v[88:91], off offset:512
	global_store_dwordx4 v[96:97], v[80:83], off offset:528
	s_mov_b32 s23, s37
	s_nop 0
	v_add_u32_e32 v80, s0, v153
	v_mov_b32_e32 v81, v137
	v_lshlrev_b64 v[80:81], 10, v[80:81]
	v_lshl_add_u64 v[80:81], v[158:159], 0, v[80:81]
	global_store_dwordx4 v[80:81], v[108:111], off
	global_store_dwordx4 v[80:81], v[100:103], off offset:16
	global_store_dwordx4 v[80:81], v[76:79], off offset:512
	global_store_dwordx4 v[80:81], v[72:75], off offset:528
	s_nop 1
	v_add_u32_e32 v72, s0, v154
	v_mov_b32_e32 v73, v137
	v_lshlrev_b64 v[72:73], 10, v[72:73]
	v_lshl_add_u64 v[72:73], v[158:159], 0, v[72:73]
	global_store_dwordx4 v[72:73], v[92:95], off
	global_store_dwordx4 v[72:73], v[84:87], off offset:16
	global_store_dwordx4 v[72:73], v[68:71], off offset:512
	global_store_dwordx4 v[72:73], v[64:67], off offset:528
	s_nop 1
	v_add_u32_e32 v64, 0x80, v136
	v_mov_b32_e32 v65, v137
	v_lshlrev_b64 v[64:65], 10, v[64:65]
	v_lshl_add_u64 v[64:65], v[158:159], 0, v[64:65]
	global_store_dwordx4 v[64:65], v[60:63], off
	global_store_dwordx4 v[64:65], v[56:59], off offset:16
	global_store_dwordx4 v[64:65], v[40:43], off offset:512
	global_store_dwordx4 v[64:65], v[32:35], off offset:528
	s_nop 1
	v_add_u32_e32 v32, 0x90, v136
	v_mov_b32_e32 v33, v137
	v_lshlrev_b64 v[32:33], 10, v[32:33]
	v_lshl_add_u64 v[32:33], v[158:159], 0, v[32:33]
	global_store_dwordx4 v[32:33], v[52:55], off
	global_store_dwordx4 v[32:33], v[48:51], off offset:16
	global_store_dwordx4 v[32:33], v[24:27], off offset:512
	global_store_dwordx4 v[32:33], v[16:19], off offset:528
	s_nop 1
	v_add_u32_e32 v16, 0xa0, v136
	v_mov_b32_e32 v17, v137
	v_lshlrev_b64 v[16:17], 10, v[16:17]
	v_lshl_add_u64 v[16:17], v[158:159], 0, v[16:17]
	v_add_u32_e32 v136, 0xb0, v136
	global_store_dwordx4 v[16:17], v[44:47], off
	global_store_dwordx4 v[16:17], v[36:39], off offset:16
	global_store_dwordx4 v[16:17], v[12:15], off offset:512
	global_store_dwordx4 v[16:17], v[8:11], off offset:528
	s_nop 1
	v_lshlrev_b64 v[8:9], 10, v[136:137]
	v_lshl_add_u64 v[8:9], v[158:159], 0, v[8:9]
	global_store_dwordx4 v[8:9], v[28:31], off
	global_store_dwordx4 v[8:9], v[20:23], off offset:16
	global_store_dwordx4 v[8:9], v[4:7], off offset:512
	global_store_dwordx4 v[8:9], v[0:3], off offset:528
	s_cbranch_vccz .LBB0_469
	s_waitcnt vmcnt(0)
	s_cmpk_gt_u32 s14, 0xff
	s_cbranch_scc1 .LBB0_474
	s_barrier

; #define PG8_STAGE(bufoff, gbase, voff) do { _Pragma("unroll") for (int _i = 0; _i < 2; ++_i) \
;         __builtin_amdgcn_global_load_lds((const unsigned*)((const char*)(gbase) + (voff)[_i]), (PG8_LAS unsigned*)(lds + (bufoff) + ldsw + _i * 8192), 16, 0, 0); } while (0)
; #define PG8_LDA(dst, b, h) do { _Pragma("unroll") for (int m = 0; m < 4; ++m) _Pragma("unroll") for (int k = 0; k < 2; ++k) dst[m][k] = *(const PG8_LAS bf16x8*)(lds + PG8_SA(b, h) + aoff + m * 2048 + k * 1024); } while (0)
; #define PG8_LDB(dst, b, h) do { _Pragma("unroll") for (int n = 0; n < 2; ++n) _Pragma("unroll") for (int k = 0; k < 2; ++k) dst[n][k] = *(const PG8_LAS bf16x8*)(lds + PG8_SB(b, h) + boff + n * 2048 + k * 1024); } while (0)
; #define PG8_MMA(ai, bj, At, Bt) do { __builtin_amdgcn_s_setprio(1); _Pragma("unroll") for (int m = 0; m < 4; ++m) _Pragma("unroll") for (int n = 0; n < 2; ++n) _Pragma("unroll") for (int k = 0; k < 2; ++k) \
;         acc[ai][bj][m][n] = __builtin_amdgcn_mfma_f32_16x16x32_bf16(Bt[n][k], At[m][k], acc[ai][bj][m][n], 0, 0, 0); __builtin_amdgcn_s_setprio(0); } while (0)
; #define PG8_WAIT_V(n) asm volatile("s_waitcnt vmcnt(" #n ")" ::: "memory")
; #define PG8_BAR __builtin_amdgcn_s_barrier()
; template <class Epi, class Sched, bool ALIGN_EPI = false, bool SP2 = false>
; __device__ __forceinline__ void gemm_phase(PG8_LAS unsigned char* lds, const Gemm g, const Sched& S, const Epi& E) {
;     ...
;         for (int t = 0; t < nt; t += 2) {
;             const bool last = (t == nt - 2);
;             const char* a1 = cA + (size_t)(t + 1) * kstep;
;             const char* a2 = last ? nA : cA + (size_t)(t + 2) * kstep; const char* b2 = last ? nB : cB + (size_t)(t + 2) * kstep;
;             const char* a3 = a2 + kstep; const char* b3 = b2 + kstep;
;             if (last && has_next) S.a_ready(nxt);
;             if constexpr (SP2) {
;             PG8_LDB(B0, 0, 0); PG8_LDB(B1, 0, 1); PG8_SCHED; PG8_LDA(At, 0, 0); PG8_STAGE(PG8_SA(1, 1), a1 + hstepA, voffA);
;             PG8_WAIT_V(8); PG8_WAIT_L(0); PG8_BAR; PG8_MMA(0, 0, At, B0); PG8_MMA(0, 1, At, B1); PG8_BAR; PG8_SCHED;
;             PG8_LDA(At, 0, 1); PG8_STAGE(PG8_SB(0, 0), b2, voffB); PG8_STAGE(PG8_SB(0, 1), b2 + hstepB, voffB); PG8_STAGE(PG8_SA(0, 0), a2, voffA);
;             PG8_WAIT_V(8); PG8_WAIT_L(0); PG8_BAR; PG8_MMA(1, 0, At, B0); PG8_MMA(1, 1, At, B1); PG8_BAR; PG8_SCHED;
.LBB0_935:
	ds_read_b128 v[120:123], v237
	ds_read_b128 v[124:127], v237 offset:1024
	ds_read_b128 v[136:139], v237 offset:2048
	ds_read_b128 v[140:143], v237 offset:3072
	ds_read_b128 v[144:147], v238
	ds_read_b128 v[148:151], v238 offset:1024
	ds_read_b128 v[152:155], v238 offset:2048
	ds_read_b128 v[156:159], v238 offset:3072
	s_add_u32 s38, s36, 0xfffc0080
	s_addc_u32 s39, s37, -1
	s_cmp_eq_u32 s58, 12
	s_cselect_b32 s41, s9, s39
	s_cselect_b32 s40, s27, s38
	s_cselect_b32 s39, s25, s57
	s_cselect_b32 s38, s35, s56
	v_lshl_add_u64 v[214:215], s[36:37], 0, v[198:199]
	s_add_i32 m0, s44, 0xc000
	ds_read_b128 v[160:163], v239
	ds_read_b128 v[164:167], v239 offset:1024
	ds_read_b128 v[168:171], v239 offset:2048
	ds_read_b128 v[172:175], v239 offset:3072
	ds_read_b128 v[176:179], v239 offset:4096
	ds_read_b128 v[180:183], v239 offset:5120
	ds_read_b128 v[206:209], v239 offset:6144
	ds_read_b128 v[210:213], v239 offset:7168
	global_load_lds_dwordx4 v[214:215], off
	v_lshl_add_u64 v[214:215], s[36:37], 0, v[200:201]
	s_add_i32 m0, s44, 0xe000
	s_nop 0
	global_load_lds_dwordx4 v[214:215], off
	s_waitcnt vmcnt(8)
	s_waitcnt lgkmcnt(0)
	s_barrier
	s_nop 0
	s_waitcnt lgkmcnt(0)
	v_mfma_f32_16x16x32_bf16 v[132:135], v[120:123], v[160:163], v[132:135]
	v_mfma_f32_16x16x32_bf16 v[128:131], v[136:139], v[160:163], v[128:131]
	v_mfma_f32_16x16x32_bf16 v[108:111], v[120:123], v[168:171], v[108:111]
	v_mfma_f32_16x16x32_bf16 v[104:107], v[136:139], v[168:171], v[104:107]
	v_mfma_f32_16x16x32_bf16 v[92:95], v[120:123], v[176:179], v[92:95]
	v_mfma_f32_16x16x32_bf16 v[88:91], v[136:139], v[176:179], v[88:91]
	v_mfma_f32_16x16x32_bf16 v[76:79], v[120:123], v[206:209], v[76:79]
	v_mfma_f32_16x16x32_bf16 v[72:75], v[136:139], v[206:209], v[72:75]
	v_mfma_f32_16x16x32_bf16 v[132:135], v[124:127], v[164:167], v[132:135]
	v_mfma_f32_16x16x32_bf16 v[128:131], v[140:143], v[164:167], v[128:131]
	v_mfma_f32_16x16x32_bf16 v[108:111], v[124:127], v[172:175], v[108:111]
	v_mfma_f32_16x16x32_bf16 v[104:107], v[140:143], v[172:175], v[104:107]
	v_mfma_f32_16x16x32_bf16 v[92:95], v[124:127], v[180:183], v[92:95]
	v_mfma_f32_16x16x32_bf16 v[88:91], v[140:143], v[180:183], v[88:91]
	v_mfma_f32_16x16x32_bf16 v[76:79], v[124:127], v[210:213], v[76:79]
	v_mfma_f32_16x16x32_bf16 v[72:75], v[140:143], v[210:213], v[72:75]
	v_mfma_f32_16x16x32_bf16 v[116:119], v[144:147], v[160:163], v[116:119]
	v_mfma_f32_16x16x32_bf16 v[112:115], v[152:155], v[160:163], v[112:115]
	v_mfma_f32_16x16x32_bf16 v[100:103], v[144:147], v[168:171], v[100:103]
	v_mfma_f32_16x16x32_bf16 v[96:99], v[152:155], v[168:171], v[96:99]
	v_mfma_f32_16x16x32_bf16 v[84:87], v[144:147], v[176:179], v[84:87]
	v_mfma_f32_16x16x32_bf16 v[80:83], v[152:155], v[176:179], v[80:83]
	v_mfma_f32_16x16x32_bf16 v[68:71], v[144:147], v[206:209], v[68:71]
	v_mfma_f32_16x16x32_bf16 v[64:67], v[152:155], v[206:209], v[64:67]
	v_mfma_f32_16x16x32_bf16 v[116:119], v[148:151], v[164:167], v[116:119]
	v_mfma_f32_16x16x32_bf16 v[112:115], v[156:159], v[164:167], v[112:115]
	v_mfma_f32_16x16x32_bf16 v[100:103], v[148:151], v[172:175], v[100:103]
	v_mfma_f32_16x16x32_bf16 v[96:99], v[156:159], v[172:175], v[96:99]
	v_mfma_f32_16x16x32_bf16 v[84:87], v[148:151], v[180:183], v[84:87]
	v_mfma_f32_16x16x32_bf16 v[80:83], v[156:159], v[180:183], v[80:83]
	v_mfma_f32_16x16x32_bf16 v[68:71], v[148:151], v[210:213], v[68:71]
	v_mfma_f32_16x16x32_bf16 v[64:67], v[156:159], v[210:213], v[64:67]
	s_nop 0
	s_barrier
	s_add_i32 s59, s53, s43
	v_lshl_add_u64 v[214:215], s[38:39], 0, v[188:189]
	s_mov_b32 m0, s59
	ds_read_b128 v[160:163], v239 offset:16384
	ds_read_b128 v[164:167], v239 offset:17408
	ds_read_b128 v[168:171], v239 offset:18432
	ds_read_b128 v[172:175], v239 offset:19456
	ds_read_b128 v[176:179], v239 offset:20480
	ds_read_b128 v[180:183], v239 offset:21504
	ds_read_b128 v[206:209], v239 offset:22528
	ds_read_b128 v[210:213], v239 offset:23552
	global_load_lds_dwordx4 v[214:215], off
	s_add_i32 m0, s59, 0x2000
	s_add_u32 s60, s38, 0x40000
	v_lshl_add_u64 v[216:217], s[38:39], 0, v[192:193]
	s_addc_u32 s61, s39, 0
	s_add_i32 s59, s54, s43
	global_load_lds_dwordx4 v[216:217], off
	v_lshl_add_u64 v[218:219], s[60:61], 0, v[188:189]
	s_mov_b32 m0, s59
	v_lshl_add_u64 v[220:221], s[40:41], 0, v[190:191]
	global_load_lds_dwordx4 v[218:219], off
	v_lshl_add_u64 v[218:219], s[60:61], 0, v[192:193]
	s_add_i32 m0, s59, 0x2000
	s_nop 0
	global_load_lds_dwordx4 v[218:219], off
	v_lshl_add_u64 v[218:219], s[40:41], 0, v[186:187]
	s_mov_b32 m0, s44
	s_nop 0
	global_load_lds_dwordx4 v[218:219], off
	s_mov_b32 m0, s45
	s_nop 0
	global_load_lds_dwordx4 v[220:221], off
	s_waitcnt vmcnt(8)
	s_waitcnt lgkmcnt(0)
	s_barrier
; #define PG8_STAGE(bufoff, gbase, voff) do { _Pragma("unroll") for (int _i = 0; _i < 2; ++_i) \
;         __builtin_amdgcn_global_load_lds((const unsigned*)((const char*)(gbase) + (voff)[_i]), (PG8_LAS unsigned*)(lds + (bufoff) + ldsw + _i * 8192), 16, 0, 0); } while (0)
; #define PG8_LDA(dst, b, h) do { _Pragma("unroll") for (int m = 0; m < 4; ++m) _Pragma("unroll") for (int k = 0; k < 2; ++k) dst[m][k] = *(const PG8_LAS bf16x8*)(lds + PG8_SA(b, h) + aoff + m * 2048 + k * 1024); } while (0)
; #define PG8_LDB(dst, b, h) do { _Pragma("unroll") for (int n = 0; n < 2; ++n) _Pragma("unroll") for (int k = 0; k < 2; ++k) dst[n][k] = *(const PG8_LAS bf16x8*)(lds + PG8_SB(b, h) + boff + n * 2048 + k * 1024); } while (0)
; #define PG8_MMA(ai, bj, At, Bt) do { __builtin_amdgcn_s_setprio(1); _Pragma("unroll") for (int m = 0; m < 4; ++m) _Pragma("unroll") for (int n = 0; n < 2; ++n) _Pragma("unroll") for (int k = 0; k < 2; ++k) \
;         acc[ai][bj][m][n] = __builtin_amdgcn_mfma_f32_16x16x32_bf16(Bt[n][k], At[m][k], acc[ai][bj][m][n], 0, 0, 0); __builtin_amdgcn_s_setprio(0); } while (0)
; #define PG8_WAIT_V(n) asm volatile("s_waitcnt vmcnt(" #n ")" ::: "memory")
; #define PG8_WAIT_L(n) asm volatile("s_waitcnt lgkmcnt(" #n ")" ::: "memory")
; #define PG8_BAR __builtin_amdgcn_s_barrier()
; #define PG8_SCHED __builtin_amdgcn_sched_barrier(0)
; template <class Epi, class Sched, bool ALIGN_EPI = false, bool SP2 = false>
; __device__ __forceinline__ void gemm_phase(PG8_LAS unsigned char* lds, const Gemm g, const Sched& S, const Epi& E) {
;     ...
;             PG8_WAIT_V(8); PG8_WAIT_L(0); PG8_BAR; PG8_MMA(1, 0, At, B0); PG8_MMA(1, 1, At, B1); PG8_BAR; PG8_SCHED;
;             PG8_LDB(B0, 1, 0); PG8_LDB(B1, 1, 1); PG8_SCHED; PG8_LDA(At, 1, 0); PG8_STAGE(PG8_SA(0, 1), a2 + hstepA, voffA);
;             PG8_WAIT_V(8); PG8_WAIT_L(0); PG8_BAR; PG8_MMA(0, 0, At, B0); PG8_MMA(0, 1, At, B1); PG8_BAR; PG8_SCHED;
	s_nop 0
	s_waitcnt lgkmcnt(0)
	v_mfma_f32_16x16x32_bf16 v[60:63], v[120:123], v[160:163], v[60:63]
	v_mfma_f32_16x16x32_bf16 v[56:59], v[136:139], v[160:163], v[56:59]
	v_mfma_f32_16x16x32_bf16 v[44:47], v[120:123], v[168:171], v[44:47]
	v_mfma_f32_16x16x32_bf16 v[40:43], v[136:139], v[168:171], v[40:43]
	v_mfma_f32_16x16x32_bf16 v[28:31], v[120:123], v[176:179], v[28:31]
	v_mfma_f32_16x16x32_bf16 v[24:27], v[136:139], v[176:179], v[24:27]
	v_mfma_f32_16x16x32_bf16 v[12:15], v[120:123], v[206:209], v[12:15]
	v_mfma_f32_16x16x32_bf16 v[8:11], v[136:139], v[206:209], v[8:11]
	v_mfma_f32_16x16x32_bf16 v[60:63], v[124:127], v[164:167], v[60:63]
	v_mfma_f32_16x16x32_bf16 v[56:59], v[140:143], v[164:167], v[56:59]
	v_mfma_f32_16x16x32_bf16 v[44:47], v[124:127], v[172:175], v[44:47]
	v_mfma_f32_16x16x32_bf16 v[40:43], v[140:143], v[172:175], v[40:43]
	v_mfma_f32_16x16x32_bf16 v[28:31], v[124:127], v[180:183], v[28:31]
	v_mfma_f32_16x16x32_bf16 v[24:27], v[140:143], v[180:183], v[24:27]
	v_mfma_f32_16x16x32_bf16 v[12:15], v[124:127], v[210:213], v[12:15]
	v_mfma_f32_16x16x32_bf16 v[8:11], v[140:143], v[210:213], v[8:11]
	v_mfma_f32_16x16x32_bf16 v[52:55], v[144:147], v[160:163], v[52:55]
	v_mfma_f32_16x16x32_bf16 v[48:51], v[152:155], v[160:163], v[48:51]
	v_mfma_f32_16x16x32_bf16 v[36:39], v[144:147], v[168:171], v[36:39]
	v_mfma_f32_16x16x32_bf16 v[32:35], v[152:155], v[168:171], v[32:35]
	v_mfma_f32_16x16x32_bf16 v[20:23], v[144:147], v[176:179], v[20:23]
	v_mfma_f32_16x16x32_bf16 v[16:19], v[152:155], v[176:179], v[16:19]
	v_mfma_f32_16x16x32_bf16 v[4:7], v[144:147], v[206:209], v[4:7]
	v_mfma_f32_16x16x32_bf16 v[0:3], v[152:155], v[206:209], v[0:3]
	v_mfma_f32_16x16x32_bf16 v[52:55], v[148:151], v[164:167], v[52:55]
	v_mfma_f32_16x16x32_bf16 v[48:51], v[156:159], v[164:167], v[48:51]
	v_mfma_f32_16x16x32_bf16 v[36:39], v[148:151], v[172:175], v[36:39]
	v_mfma_f32_16x16x32_bf16 v[32:35], v[156:159], v[172:175], v[32:35]
	v_mfma_f32_16x16x32_bf16 v[20:23], v[148:151], v[180:183], v[20:23]
	v_mfma_f32_16x16x32_bf16 v[16:19], v[156:159], v[180:183], v[16:19]
	v_mfma_f32_16x16x32_bf16 v[4:7], v[148:151], v[210:213], v[4:7]
	v_mfma_f32_16x16x32_bf16 v[0:3], v[156:159], v[210:213], v[0:3]
	s_nop 0
	s_barrier
	s_add_i32 s59, 0, 0x18000
	s_add_i32 s60, 0, 0x1c000
	v_add_u32_e32 v140, s59, v234
	v_add_u32_e32 v156, s60, v234
	ds_read_b128 v[120:123], v140
	ds_read_b128 v[124:127], v140 offset:1024
	ds_read_b128 v[136:139], v140 offset:2048
	ds_read_b128 v[140:143], v140 offset:3072
	ds_read_b128 v[144:147], v156
	ds_read_b128 v[148:151], v156 offset:1024
	ds_read_b128 v[152:155], v156 offset:2048
	ds_read_b128 v[156:159], v156 offset:3072
	s_add_u32 s40, s40, 0x40000
	s_addc_u32 s41, s41, 0
	s_mov_b32 m0, s46
	v_lshl_add_u64 v[222:223], s[40:41], 0, v[186:187]
	ds_read_b128 v[160:163], v239 offset:32768
	ds_read_b128 v[164:167], v239 offset:33792
	ds_read_b128 v[168:171], v239 offset:34816
	ds_read_b128 v[172:175], v239 offset:35840
	ds_read_b128 v[176:179], v239 offset:36864
	ds_read_b128 v[180:183], v239 offset:37888
	ds_read_b128 v[206:209], v239 offset:38912
	ds_read_b128 v[210:213], v239 offset:39936
	global_load_lds_dwordx4 v[222:223], off
	v_lshl_add_u64 v[222:223], s[40:41], 0, v[190:191]
	s_mov_b32 m0, s47
	s_nop 0
	global_load_lds_dwordx4 v[222:223], off
	s_waitcnt vmcnt(8)
	s_waitcnt lgkmcnt(0)
	s_barrier
	s_nop 0
	s_waitcnt lgkmcnt(0)
	v_mfma_f32_16x16x32_bf16 v[132:135], v[120:123], v[160:163], v[132:135]
	v_mfma_f32_16x16x32_bf16 v[128:131], v[136:139], v[160:163], v[128:131]
	v_mfma_f32_16x16x32_bf16 v[108:111], v[120:123], v[168:171], v[108:111]
	v_mfma_f32_16x16x32_bf16 v[104:107], v[136:139], v[168:171], v[104:107]
	v_mfma_f32_16x16x32_bf16 v[92:95], v[120:123], v[176:179], v[92:95]
	v_mfma_f32_16x16x32_bf16 v[88:91], v[136:139], v[176:179], v[88:91]
	v_mfma_f32_16x16x32_bf16 v[76:79], v[120:123], v[206:209], v[76:79]
	v_mfma_f32_16x16x32_bf16 v[72:75], v[136:139], v[206:209], v[72:75]
	v_mfma_f32_16x16x32_bf16 v[132:135], v[124:127], v[164:167], v[132:135]
	v_mfma_f32_16x16x32_bf16 v[128:131], v[140:143], v[164:167], v[128:131]
	v_mfma_f32_16x16x32_bf16 v[108:111], v[124:127], v[172:175], v[108:111]
	v_mfma_f32_16x16x32_bf16 v[104:107], v[140:143], v[172:175], v[104:107]
	v_mfma_f32_16x16x32_bf16 v[92:95], v[124:127], v[180:183], v[92:95]
	v_mfma_f32_16x16x32_bf16 v[88:91], v[140:143], v[180:183], v[88:91]
	v_mfma_f32_16x16x32_bf16 v[76:79], v[124:127], v[210:213], v[76:79]
	v_mfma_f32_16x16x32_bf16 v[72:75], v[140:143], v[210:213], v[72:75]
	v_mfma_f32_16x16x32_bf16 v[116:119], v[144:147], v[160:163], v[116:119]
	v_mfma_f32_16x16x32_bf16 v[112:115], v[152:155], v[160:163], v[112:115]
	v_mfma_f32_16x16x32_bf16 v[100:103], v[144:147], v[168:171], v[100:103]
	v_mfma_f32_16x16x32_bf16 v[96:99], v[152:155], v[168:171], v[96:99]
	v_mfma_f32_16x16x32_bf16 v[84:87], v[144:147], v[176:179], v[84:87]
	v_mfma_f32_16x16x32_bf16 v[80:83], v[152:155], v[176:179], v[80:83]
	v_mfma_f32_16x16x32_bf16 v[68:71], v[144:147], v[206:209], v[68:71]
	v_mfma_f32_16x16x32_bf16 v[64:67], v[152:155], v[206:209], v[64:67]
	v_mfma_f32_16x16x32_bf16 v[116:119], v[148:151], v[164:167], v[116:119]
	v_mfma_f32_16x16x32_bf16 v[112:115], v[156:159], v[164:167], v[112:115]
	v_mfma_f32_16x16x32_bf16 v[100:103], v[148:151], v[172:175], v[100:103]
	v_mfma_f32_16x16x32_bf16 v[96:99], v[156:159], v[172:175], v[96:99]
	v_mfma_f32_16x16x32_bf16 v[84:87], v[148:151], v[180:183], v[84:87]
	v_mfma_f32_16x16x32_bf16 v[80:83], v[156:159], v[180:183], v[80:83]
	v_mfma_f32_16x16x32_bf16 v[68:71], v[148:151], v[210:213], v[68:71]
	v_mfma_f32_16x16x32_bf16 v[64:67], v[156:159], v[210:213], v[64:67]
	s_nop 0
	s_barrier
; #define PG8_STAGE(bufoff, gbase, voff) do { _Pragma("unroll") for (int _i = 0; _i < 2; ++_i) \
;         __builtin_amdgcn_global_load_lds((const unsigned*)((const char*)(gbase) + (voff)[_i]), (PG8_LAS unsigned*)(lds + (bufoff) + ldsw + _i * 8192), 16, 0, 0); } while (0)
; #define PG8_LDA(dst, b, h) do { _Pragma("unroll") for (int m = 0; m < 4; ++m) _Pragma("unroll") for (int k = 0; k < 2; ++k) dst[m][k] = *(const PG8_LAS bf16x8*)(lds + PG8_SA(b, h) + aoff + m * 2048 + k * 1024); } while (0)
; #define PG8_MMA(ai, bj, At, Bt) do { __builtin_amdgcn_s_setprio(1); _Pragma("unroll") for (int m = 0; m < 4; ++m) _Pragma("unroll") for (int n = 0; n < 2; ++n) _Pragma("unroll") for (int k = 0; k < 2; ++k) \
;         acc[ai][bj][m][n] = __builtin_amdgcn_mfma_f32_16x16x32_bf16(Bt[n][k], At[m][k], acc[ai][bj][m][n], 0, 0, 0); __builtin_amdgcn_s_setprio(0); } while (0)
; #define PG8_WAIT_V(n) asm volatile("s_waitcnt vmcnt(" #n ")" ::: "memory")
; #define PG8_WAIT_L(n) asm volatile("s_waitcnt lgkmcnt(" #n ")" ::: "memory")
; #define PG8_BAR __builtin_amdgcn_s_barrier()
; #define PG8_SCHED __builtin_amdgcn_sched_barrier(0)
; template <class Epi, class Sched, bool ALIGN_EPI = false, bool SP2 = false>
; __device__ __forceinline__ void gemm_phase(PG8_LAS unsigned char* lds, const Gemm g, const Sched& S, const Epi& E) {
;     ...
;         for (int t = 0; t < nt; t += 2) {
;             const bool last = (t == nt - 2);
;             const char* a1 = cA + (size_t)(t + 1) * kstep;
;             const char* a2 = last ? nA : cA + (size_t)(t + 2) * kstep; const char* b2 = last ? nB : cB + (size_t)(t + 2) * kstep;
;             const char* a3 = a2 + kstep; const char* b3 = b2 + kstep;
;             if (last && has_next) S.a_ready(nxt);
;     ...
;             PG8_LDA(At, 1, 1); PG8_STAGE(PG8_SB(1, 0), b3, voffB); PG8_STAGE(PG8_SB(1, 1), b3 + hstepB, voffB); PG8_STAGE(PG8_SA(1, 0), a3, voffA);
;             PG8_WAIT_V(8); PG8_WAIT_L(0); PG8_BAR; PG8_MMA(1, 0, At, B0); PG8_MMA(1, 1, At, B1); PG8_BAR; PG8_SCHED;
	s_add_i32 s40, s59, s43
	v_lshl_add_u64 v[214:215], v[214:215], 0, s[20:21]
	s_mov_b32 m0, s40
	ds_read_b128 v[160:163], v239 offset:49152
	ds_read_b128 v[164:167], v239 offset:50176
	ds_read_b128 v[168:171], v239 offset:51200
	ds_read_b128 v[172:175], v239 offset:52224
	ds_read_b128 v[176:179], v239 offset:53248
	ds_read_b128 v[180:183], v239 offset:54272
	ds_read_b128 v[206:209], v239 offset:55296
	ds_read_b128 v[210:213], v239 offset:56320
	global_load_lds_dwordx4 v[214:215], off
	s_add_i32 m0, s40, 0x2000
	s_add_u32 s38, s38, 0x40080
	v_lshl_add_u64 v[214:215], v[216:217], 0, s[20:21]
	s_addc_u32 s39, s39, 0
	s_add_i32 s40, s60, s43
	global_load_lds_dwordx4 v[214:215], off
	v_lshl_add_u64 v[214:215], s[38:39], 0, v[188:189]
	s_mov_b32 m0, s40
	s_nop 0
	global_load_lds_dwordx4 v[214:215], off
	v_lshl_add_u64 v[214:215], s[38:39], 0, v[192:193]
	s_add_i32 m0, s40, 0x2000
	s_nop 0
	global_load_lds_dwordx4 v[214:215], off
	v_lshl_add_u64 v[214:215], v[218:219], 0, s[20:21]
	s_mov_b32 m0, s48
	s_nop 0
	global_load_lds_dwordx4 v[214:215], off
	v_lshl_add_u64 v[214:215], v[220:221], 0, s[20:21]
	s_mov_b32 m0, s49
	s_nop 0
	global_load_lds_dwordx4 v[214:215], off
	s_waitcnt vmcnt(8)
	s_waitcnt lgkmcnt(0)
	s_barrier
	s_nop 0
	s_waitcnt lgkmcnt(0)
	v_mfma_f32_16x16x32_bf16 v[60:63], v[120:123], v[160:163], v[60:63]
	v_mfma_f32_16x16x32_bf16 v[56:59], v[136:139], v[160:163], v[56:59]
	v_mfma_f32_16x16x32_bf16 v[44:47], v[120:123], v[168:171], v[44:47]
	v_mfma_f32_16x16x32_bf16 v[40:43], v[136:139], v[168:171], v[40:43]
	v_mfma_f32_16x16x32_bf16 v[28:31], v[120:123], v[176:179], v[28:31]
	v_mfma_f32_16x16x32_bf16 v[24:27], v[136:139], v[176:179], v[24:27]
	v_mfma_f32_16x16x32_bf16 v[12:15], v[120:123], v[206:209], v[12:15]
	v_mfma_f32_16x16x32_bf16 v[8:11], v[136:139], v[206:209], v[8:11]
	v_mfma_f32_16x16x32_bf16 v[60:63], v[124:127], v[164:167], v[60:63]
	v_mfma_f32_16x16x32_bf16 v[56:59], v[140:143], v[164:167], v[56:59]
	v_mfma_f32_16x16x32_bf16 v[44:47], v[124:127], v[172:175], v[44:47]
	v_mfma_f32_16x16x32_bf16 v[40:43], v[140:143], v[172:175], v[40:43]
	v_mfma_f32_16x16x32_bf16 v[28:31], v[124:127], v[180:183], v[28:31]
	v_mfma_f32_16x16x32_bf16 v[24:27], v[140:143], v[180:183], v[24:27]
	v_mfma_f32_16x16x32_bf16 v[12:15], v[124:127], v[210:213], v[12:15]
	v_mfma_f32_16x16x32_bf16 v[8:11], v[140:143], v[210:213], v[8:11]
	v_mfma_f32_16x16x32_bf16 v[52:55], v[144:147], v[160:163], v[52:55]
	v_mfma_f32_16x16x32_bf16 v[48:51], v[152:155], v[160:163], v[48:51]
	v_mfma_f32_16x16x32_bf16 v[36:39], v[144:147], v[168:171], v[36:39]
	v_mfma_f32_16x16x32_bf16 v[32:35], v[152:155], v[168:171], v[32:35]
	v_mfma_f32_16x16x32_bf16 v[20:23], v[144:147], v[176:179], v[20:23]
	v_mfma_f32_16x16x32_bf16 v[16:19], v[152:155], v[176:179], v[16:19]
	v_mfma_f32_16x16x32_bf16 v[4:7], v[144:147], v[206:209], v[4:7]
	v_mfma_f32_16x16x32_bf16 v[0:3], v[152:155], v[206:209], v[0:3]
	v_mfma_f32_16x16x32_bf16 v[52:55], v[148:151], v[164:167], v[52:55]
	v_mfma_f32_16x16x32_bf16 v[48:51], v[156:159], v[164:167], v[48:51]
	v_mfma_f32_16x16x32_bf16 v[36:39], v[148:151], v[172:175], v[36:39]
	v_mfma_f32_16x16x32_bf16 v[32:35], v[156:159], v[172:175], v[32:35]
	v_mfma_f32_16x16x32_bf16 v[20:23], v[148:151], v[180:183], v[20:23]
	v_mfma_f32_16x16x32_bf16 v[16:19], v[156:159], v[180:183], v[16:19]
	v_mfma_f32_16x16x32_bf16 v[4:7], v[148:151], v[210:213], v[4:7]
	v_mfma_f32_16x16x32_bf16 v[0:3], v[156:159], v[210:213], v[0:3]
	s_nop 0
	s_barrier
	s_add_i32 s58, s58, 2
	s_add_u32 s36, s36, 0x100
	s_addc_u32 s37, s37, 0
	s_add_u32 s56, s56, 0x100
	s_addc_u32 s57, s57, 0
	s_cmp_gt_u32 s58, 13
	s_cbranch_scc0 .LBB0_935
	s_and_b64 vcc, exec, s[22:23]
	s_cbranch_vccz .LBB0_938
	s_barrier

; #define PG8_STAGE(bufoff, gbase, voff) do { _Pragma("unroll") for (int _i = 0; _i < 2; ++_i) \
;         __builtin_amdgcn_global_load_lds((const unsigned*)((const char*)(gbase) + (voff)[_i]), (PG8_LAS unsigned*)(lds + (bufoff) + ldsw + _i * 8192), 16, 0, 0); } while (0)
; #define PG8_LDA(dst, b, h) do { _Pragma("unroll") for (int m = 0; m < 4; ++m) _Pragma("unroll") for (int k = 0; k < 2; ++k) dst[m][k] = *(const PG8_LAS bf16x8*)(lds + PG8_SA(b, h) + aoff + m * 2048 + k * 1024); } while (0)
; #define PG8_LDB(dst, b, h) do { _Pragma("unroll") for (int n = 0; n < 2; ++n) _Pragma("unroll") for (int k = 0; k < 2; ++k) dst[n][k] = *(const PG8_LAS bf16x8*)(lds + PG8_SB(b, h) + boff + n * 2048 + k * 1024); } while (0)
; #define PG8_MMA(ai, bj, At, Bt) do { __builtin_amdgcn_s_setprio(1); _Pragma("unroll") for (int m = 0; m < 4; ++m) _Pragma("unroll") for (int n = 0; n < 2; ++n) _Pragma("unroll") for (int k = 0; k < 2; ++k) \
;         acc[ai][bj][m][n] = __builtin_amdgcn_mfma_f32_16x16x32_bf16(Bt[n][k], At[m][k], acc[ai][bj][m][n], 0, 0, 0); __builtin_amdgcn_s_setprio(0); } while (0)
; #define PG8_WAIT_V(n) asm volatile("s_waitcnt vmcnt(" #n ")" ::: "memory")
; #define PG8_BAR __builtin_amdgcn_s_barrier()
; template <class Epi, class Sched, bool ALIGN_EPI = false, bool SP2 = false>
; __device__ __forceinline__ void gemm_phase(PG8_LAS unsigned char* lds, const Gemm g, const Sched& S, const Epi& E) {
;     ...
;         for (int t = 0; t < nt; t += 2) {
;             const bool last = (t == nt - 2);
;             const char* a1 = cA + (size_t)(t + 1) * kstep;
;             const char* a2 = last ? nA : cA + (size_t)(t + 2) * kstep; const char* b2 = last ? nB : cB + (size_t)(t + 2) * kstep;
;             const char* a3 = a2 + kstep; const char* b3 = b2 + kstep;
;             if (last && has_next) S.a_ready(nxt);
;             if constexpr (SP2) {
;             PG8_LDB(B0, 0, 0); PG8_LDB(B1, 0, 1); PG8_SCHED; PG8_LDA(At, 0, 0); PG8_STAGE(PG8_SA(1, 1), a1 + hstepA, voffA);
;             PG8_WAIT_V(8); PG8_WAIT_L(0); PG8_BAR; PG8_MMA(0, 0, At, B0); PG8_MMA(0, 1, At, B1); PG8_BAR; PG8_SCHED;
;             PG8_LDA(At, 0, 1); PG8_STAGE(PG8_SB(0, 0), b2, voffB); PG8_STAGE(PG8_SB(0, 1), b2 + hstepB, voffB); PG8_STAGE(PG8_SA(0, 0), a2, voffA);
;             PG8_WAIT_V(8); PG8_WAIT_L(0); PG8_BAR; PG8_MMA(1, 0, At, B0); PG8_MMA(1, 1, At, B1); PG8_BAR; PG8_SCHED;
.LBB0_1007:
	ds_read_b128 v[128:131], v176
	ds_read_b128 v[132:135], v176 offset:1024
	ds_read_b128 v[136:139], v176 offset:2048
	ds_read_b128 v[140:143], v176 offset:3072
	ds_read_b128 v[162:165], v177
	ds_read_b128 v[166:169], v177 offset:1024
	ds_read_b128 v[170:173], v177 offset:2048
	ds_read_b128 v[180:183], v177 offset:3072
	s_add_u32 s36, s34, 0xfffc0080
	s_addc_u32 s37, s35, -1
	s_cmp_eq_u32 s56, 12
	s_cselect_b32 s39, s25, s37
	s_cselect_b32 s38, s52, s36
	s_cselect_b32 s37, s23, s55
	s_cselect_b32 s36, s53, s54
	v_lshl_add_u64 v[218:219], s[34:35], 0, v[154:155]
	s_add_i32 m0, s41, 0xc000
	ds_read_b128 v[186:189], v178
	ds_read_b128 v[190:193], v178 offset:1024
	ds_read_b128 v[194:197], v178 offset:2048
	ds_read_b128 v[198:201], v178 offset:3072
	ds_read_b128 v[202:205], v178 offset:4096
	ds_read_b128 v[206:209], v178 offset:5120
	ds_read_b128 v[210:213], v178 offset:6144
	ds_read_b128 v[214:217], v178 offset:7168
	global_load_lds_dwordx4 v[218:219], off
	v_lshl_add_u64 v[218:219], s[34:35], 0, v[156:157]
	s_add_i32 m0, s41, 0xe000
	s_nop 0
	global_load_lds_dwordx4 v[218:219], off
	s_waitcnt vmcnt(8)
	s_waitcnt lgkmcnt(0)
	s_barrier
	s_nop 0
	s_waitcnt lgkmcnt(0)
	v_mfma_f32_16x16x32_bf16 v[124:127], v[128:131], v[186:189], v[124:127]
	v_mfma_f32_16x16x32_bf16 v[120:123], v[136:139], v[186:189], v[120:123]
	v_mfma_f32_16x16x32_bf16 v[108:111], v[128:131], v[194:197], v[108:111]
	v_mfma_f32_16x16x32_bf16 v[104:107], v[136:139], v[194:197], v[104:107]
	v_mfma_f32_16x16x32_bf16 v[92:95], v[128:131], v[202:205], v[92:95]
	v_mfma_f32_16x16x32_bf16 v[88:91], v[136:139], v[202:205], v[88:91]
	v_mfma_f32_16x16x32_bf16 v[76:79], v[128:131], v[210:213], v[76:79]
	v_mfma_f32_16x16x32_bf16 v[72:75], v[136:139], v[210:213], v[72:75]
	v_mfma_f32_16x16x32_bf16 v[124:127], v[132:135], v[190:193], v[124:127]
	v_mfma_f32_16x16x32_bf16 v[120:123], v[140:143], v[190:193], v[120:123]
	v_mfma_f32_16x16x32_bf16 v[108:111], v[132:135], v[198:201], v[108:111]
	v_mfma_f32_16x16x32_bf16 v[104:107], v[140:143], v[198:201], v[104:107]
	v_mfma_f32_16x16x32_bf16 v[92:95], v[132:135], v[206:209], v[92:95]
	v_mfma_f32_16x16x32_bf16 v[88:91], v[140:143], v[206:209], v[88:91]
	v_mfma_f32_16x16x32_bf16 v[76:79], v[132:135], v[214:217], v[76:79]
	v_mfma_f32_16x16x32_bf16 v[72:75], v[140:143], v[214:217], v[72:75]
	v_mfma_f32_16x16x32_bf16 v[116:119], v[162:165], v[186:189], v[116:119]
	v_mfma_f32_16x16x32_bf16 v[112:115], v[170:173], v[186:189], v[112:115]
	v_mfma_f32_16x16x32_bf16 v[100:103], v[162:165], v[194:197], v[100:103]
	v_mfma_f32_16x16x32_bf16 v[96:99], v[170:173], v[194:197], v[96:99]
	v_mfma_f32_16x16x32_bf16 v[84:87], v[162:165], v[202:205], v[84:87]
	v_mfma_f32_16x16x32_bf16 v[80:83], v[170:173], v[202:205], v[80:83]
	v_mfma_f32_16x16x32_bf16 v[68:71], v[162:165], v[210:213], v[68:71]
	v_mfma_f32_16x16x32_bf16 v[64:67], v[170:173], v[210:213], v[64:67]
	v_mfma_f32_16x16x32_bf16 v[116:119], v[166:169], v[190:193], v[116:119]
	v_mfma_f32_16x16x32_bf16 v[112:115], v[180:183], v[190:193], v[112:115]
	v_mfma_f32_16x16x32_bf16 v[100:103], v[166:169], v[198:201], v[100:103]
	v_mfma_f32_16x16x32_bf16 v[96:99], v[180:183], v[198:201], v[96:99]
	v_mfma_f32_16x16x32_bf16 v[84:87], v[166:169], v[206:209], v[84:87]
	v_mfma_f32_16x16x32_bf16 v[80:83], v[180:183], v[206:209], v[80:83]
	v_mfma_f32_16x16x32_bf16 v[68:71], v[166:169], v[214:217], v[68:71]
	v_mfma_f32_16x16x32_bf16 v[64:67], v[180:183], v[214:217], v[64:67]
	s_nop 0
	s_barrier
	s_add_i32 s57, s48, s40
	v_lshl_add_u64 v[218:219], s[36:37], 0, v[146:147]
	s_mov_b32 m0, s57
	ds_read_b128 v[186:189], v178 offset:16384
	ds_read_b128 v[190:193], v178 offset:17408
	ds_read_b128 v[194:197], v178 offset:18432
	ds_read_b128 v[198:201], v178 offset:19456
	ds_read_b128 v[202:205], v178 offset:20480
	ds_read_b128 v[206:209], v178 offset:21504
	ds_read_b128 v[210:213], v178 offset:22528
	ds_read_b128 v[214:217], v178 offset:23552
	global_load_lds_dwordx4 v[218:219], off
	s_add_i32 m0, s57, 0x2000
	s_add_u32 s58, s36, 0x40000
	v_lshl_add_u64 v[220:221], s[36:37], 0, v[150:151]
	s_addc_u32 s59, s37, 0
	s_add_i32 s57, s49, s40
	global_load_lds_dwordx4 v[220:221], off
	v_lshl_add_u64 v[222:223], s[58:59], 0, v[146:147]
	s_mov_b32 m0, s57
	v_lshl_add_u64 v[224:225], s[38:39], 0, v[148:149]
	global_load_lds_dwordx4 v[222:223], off
	v_lshl_add_u64 v[222:223], s[58:59], 0, v[150:151]
	s_add_i32 m0, s57, 0x2000
	s_nop 0
	global_load_lds_dwordx4 v[222:223], off
	v_lshl_add_u64 v[222:223], s[38:39], 0, v[144:145]
	s_mov_b32 m0, s41
	s_nop 0
	global_load_lds_dwordx4 v[222:223], off
	s_mov_b32 m0, s42
	s_nop 0
	global_load_lds_dwordx4 v[224:225], off
	s_waitcnt vmcnt(8)
	s_waitcnt lgkmcnt(0)
	s_barrier
; #define PG8_STAGE(bufoff, gbase, voff) do { _Pragma("unroll") for (int _i = 0; _i < 2; ++_i) \
;         __builtin_amdgcn_global_load_lds((const unsigned*)((const char*)(gbase) + (voff)[_i]), (PG8_LAS unsigned*)(lds + (bufoff) + ldsw + _i * 8192), 16, 0, 0); } while (0)
; #define PG8_LDA(dst, b, h) do { _Pragma("unroll") for (int m = 0; m < 4; ++m) _Pragma("unroll") for (int k = 0; k < 2; ++k) dst[m][k] = *(const PG8_LAS bf16x8*)(lds + PG8_SA(b, h) + aoff + m * 2048 + k * 1024); } while (0)
; #define PG8_LDB(dst, b, h) do { _Pragma("unroll") for (int n = 0; n < 2; ++n) _Pragma("unroll") for (int k = 0; k < 2; ++k) dst[n][k] = *(const PG8_LAS bf16x8*)(lds + PG8_SB(b, h) + boff + n * 2048 + k * 1024); } while (0)
; #define PG8_MMA(ai, bj, At, Bt) do { __builtin_amdgcn_s_setprio(1); _Pragma("unroll") for (int m = 0; m < 4; ++m) _Pragma("unroll") for (int n = 0; n < 2; ++n) _Pragma("unroll") for (int k = 0; k < 2; ++k) \
;         acc[ai][bj][m][n] = __builtin_amdgcn_mfma_f32_16x16x32_bf16(Bt[n][k], At[m][k], acc[ai][bj][m][n], 0, 0, 0); __builtin_amdgcn_s_setprio(0); } while (0)
; #define PG8_WAIT_V(n) asm volatile("s_waitcnt vmcnt(" #n ")" ::: "memory")
; #define PG8_WAIT_L(n) asm volatile("s_waitcnt lgkmcnt(" #n ")" ::: "memory")
; #define PG8_BAR __builtin_amdgcn_s_barrier()
; #define PG8_SCHED __builtin_amdgcn_sched_barrier(0)
; template <class Epi, class Sched, bool ALIGN_EPI = false, bool SP2 = false>
; __device__ __forceinline__ void gemm_phase(PG8_LAS unsigned char* lds, const Gemm g, const Sched& S, const Epi& E) {
;     ...
;             PG8_WAIT_V(8); PG8_WAIT_L(0); PG8_BAR; PG8_MMA(1, 0, At, B0); PG8_MMA(1, 1, At, B1); PG8_BAR; PG8_SCHED;
;             PG8_LDB(B0, 1, 0); PG8_LDB(B1, 1, 1); PG8_SCHED; PG8_LDA(At, 1, 0); PG8_STAGE(PG8_SA(0, 1), a2 + hstepA, voffA);
;             PG8_WAIT_V(8); PG8_WAIT_L(0); PG8_BAR; PG8_MMA(0, 0, At, B0); PG8_MMA(0, 1, At, B1); PG8_BAR; PG8_SCHED;
	s_nop 0
	s_waitcnt lgkmcnt(0)
	v_mfma_f32_16x16x32_bf16 v[60:63], v[128:131], v[186:189], v[60:63]
	v_mfma_f32_16x16x32_bf16 v[56:59], v[136:139], v[186:189], v[56:59]
	v_mfma_f32_16x16x32_bf16 v[44:47], v[128:131], v[194:197], v[44:47]
	v_mfma_f32_16x16x32_bf16 v[40:43], v[136:139], v[194:197], v[40:43]
	v_mfma_f32_16x16x32_bf16 v[28:31], v[128:131], v[202:205], v[28:31]
	v_mfma_f32_16x16x32_bf16 v[24:27], v[136:139], v[202:205], v[24:27]
	v_mfma_f32_16x16x32_bf16 v[12:15], v[128:131], v[210:213], v[12:15]
	v_mfma_f32_16x16x32_bf16 v[8:11], v[136:139], v[210:213], v[8:11]
	v_mfma_f32_16x16x32_bf16 v[60:63], v[132:135], v[190:193], v[60:63]
	v_mfma_f32_16x16x32_bf16 v[56:59], v[140:143], v[190:193], v[56:59]
	v_mfma_f32_16x16x32_bf16 v[44:47], v[132:135], v[198:201], v[44:47]
	v_mfma_f32_16x16x32_bf16 v[40:43], v[140:143], v[198:201], v[40:43]
	v_mfma_f32_16x16x32_bf16 v[28:31], v[132:135], v[206:209], v[28:31]
	v_mfma_f32_16x16x32_bf16 v[24:27], v[140:143], v[206:209], v[24:27]
	v_mfma_f32_16x16x32_bf16 v[12:15], v[132:135], v[214:217], v[12:15]
	v_mfma_f32_16x16x32_bf16 v[8:11], v[140:143], v[214:217], v[8:11]
	v_mfma_f32_16x16x32_bf16 v[52:55], v[162:165], v[186:189], v[52:55]
	v_mfma_f32_16x16x32_bf16 v[48:51], v[170:173], v[186:189], v[48:51]
	v_mfma_f32_16x16x32_bf16 v[36:39], v[162:165], v[194:197], v[36:39]
	v_mfma_f32_16x16x32_bf16 v[32:35], v[170:173], v[194:197], v[32:35]
	v_mfma_f32_16x16x32_bf16 v[20:23], v[162:165], v[202:205], v[20:23]
	v_mfma_f32_16x16x32_bf16 v[16:19], v[170:173], v[202:205], v[16:19]
	v_mfma_f32_16x16x32_bf16 v[4:7], v[162:165], v[210:213], v[4:7]
	v_mfma_f32_16x16x32_bf16 v[0:3], v[170:173], v[210:213], v[0:3]
	v_mfma_f32_16x16x32_bf16 v[52:55], v[166:169], v[190:193], v[52:55]
	v_mfma_f32_16x16x32_bf16 v[48:51], v[180:183], v[190:193], v[48:51]
	v_mfma_f32_16x16x32_bf16 v[36:39], v[166:169], v[198:201], v[36:39]
	v_mfma_f32_16x16x32_bf16 v[32:35], v[180:183], v[198:201], v[32:35]
	v_mfma_f32_16x16x32_bf16 v[20:23], v[166:169], v[206:209], v[20:23]
	v_mfma_f32_16x16x32_bf16 v[16:19], v[180:183], v[206:209], v[16:19]
	v_mfma_f32_16x16x32_bf16 v[4:7], v[166:169], v[214:217], v[4:7]
	v_mfma_f32_16x16x32_bf16 v[0:3], v[180:183], v[214:217], v[0:3]
	s_nop 0
	s_barrier
	s_add_i32 s57, 0, 0x18000
	s_add_i32 s58, 0, 0x1c000
	v_add_u32_e32 v140, s57, v175
	v_add_u32_e32 v179, s58, v175
	ds_read_b128 v[128:131], v140
	ds_read_b128 v[132:135], v140 offset:1024
	ds_read_b128 v[136:139], v140 offset:2048
	ds_read_b128 v[140:143], v140 offset:3072
	ds_read_b128 v[162:165], v179
	ds_read_b128 v[166:169], v179 offset:1024
	ds_read_b128 v[170:173], v179 offset:2048
	ds_read_b128 v[180:183], v179 offset:3072
	s_add_u32 s38, s38, 0x40000
	s_addc_u32 s39, s39, 0
	s_mov_b32 m0, s43
	v_lshl_add_u64 v[226:227], s[38:39], 0, v[144:145]
	ds_read_b128 v[186:189], v178 offset:32768
	ds_read_b128 v[190:193], v178 offset:33792
	ds_read_b128 v[194:197], v178 offset:34816
	ds_read_b128 v[198:201], v178 offset:35840
	ds_read_b128 v[202:205], v178 offset:36864
	ds_read_b128 v[206:209], v178 offset:37888
	ds_read_b128 v[210:213], v178 offset:38912
	ds_read_b128 v[214:217], v178 offset:39936
	global_load_lds_dwordx4 v[226:227], off
	v_lshl_add_u64 v[226:227], s[38:39], 0, v[148:149]
	s_mov_b32 m0, s44
	s_nop 0
	global_load_lds_dwordx4 v[226:227], off
	s_waitcnt vmcnt(8)
	s_waitcnt lgkmcnt(0)
	s_barrier
	s_nop 0
	s_waitcnt lgkmcnt(0)
	v_mfma_f32_16x16x32_bf16 v[124:127], v[128:131], v[186:189], v[124:127]
	v_mfma_f32_16x16x32_bf16 v[120:123], v[136:139], v[186:189], v[120:123]
	v_mfma_f32_16x16x32_bf16 v[108:111], v[128:131], v[194:197], v[108:111]
	v_mfma_f32_16x16x32_bf16 v[104:107], v[136:139], v[194:197], v[104:107]
	v_mfma_f32_16x16x32_bf16 v[92:95], v[128:131], v[202:205], v[92:95]
	v_mfma_f32_16x16x32_bf16 v[88:91], v[136:139], v[202:205], v[88:91]
	v_mfma_f32_16x16x32_bf16 v[76:79], v[128:131], v[210:213], v[76:79]
	v_mfma_f32_16x16x32_bf16 v[72:75], v[136:139], v[210:213], v[72:75]
	v_mfma_f32_16x16x32_bf16 v[124:127], v[132:135], v[190:193], v[124:127]
	v_mfma_f32_16x16x32_bf16 v[120:123], v[140:143], v[190:193], v[120:123]
	v_mfma_f32_16x16x32_bf16 v[108:111], v[132:135], v[198:201], v[108:111]
	v_mfma_f32_16x16x32_bf16 v[104:107], v[140:143], v[198:201], v[104:107]
	v_mfma_f32_16x16x32_bf16 v[92:95], v[132:135], v[206:209], v[92:95]
	v_mfma_f32_16x16x32_bf16 v[88:91], v[140:143], v[206:209], v[88:91]
	v_mfma_f32_16x16x32_bf16 v[76:79], v[132:135], v[214:217], v[76:79]
	v_mfma_f32_16x16x32_bf16 v[72:75], v[140:143], v[214:217], v[72:75]
	v_mfma_f32_16x16x32_bf16 v[116:119], v[162:165], v[186:189], v[116:119]
	v_mfma_f32_16x16x32_bf16 v[112:115], v[170:173], v[186:189], v[112:115]
	v_mfma_f32_16x16x32_bf16 v[100:103], v[162:165], v[194:197], v[100:103]
	v_mfma_f32_16x16x32_bf16 v[96:99], v[170:173], v[194:197], v[96:99]
	v_mfma_f32_16x16x32_bf16 v[84:87], v[162:165], v[202:205], v[84:87]
	v_mfma_f32_16x16x32_bf16 v[80:83], v[170:173], v[202:205], v[80:83]
	v_mfma_f32_16x16x32_bf16 v[68:71], v[162:165], v[210:213], v[68:71]
	v_mfma_f32_16x16x32_bf16 v[64:67], v[170:173], v[210:213], v[64:67]
	v_mfma_f32_16x16x32_bf16 v[116:119], v[166:169], v[190:193], v[116:119]
	v_mfma_f32_16x16x32_bf16 v[112:115], v[180:183], v[190:193], v[112:115]
	v_mfma_f32_16x16x32_bf16 v[100:103], v[166:169], v[198:201], v[100:103]
	v_mfma_f32_16x16x32_bf16 v[96:99], v[180:183], v[198:201], v[96:99]
	v_mfma_f32_16x16x32_bf16 v[84:87], v[166:169], v[206:209], v[84:87]
	v_mfma_f32_16x16x32_bf16 v[80:83], v[180:183], v[206:209], v[80:83]
	v_mfma_f32_16x16x32_bf16 v[68:71], v[166:169], v[214:217], v[68:71]
	v_mfma_f32_16x16x32_bf16 v[64:67], v[180:183], v[214:217], v[64:67]
	s_nop 0
	s_barrier
; #define PG8_STAGE(bufoff, gbase, voff) do { _Pragma("unroll") for (int _i = 0; _i < 2; ++_i) \
;         __builtin_amdgcn_global_load_lds((const unsigned*)((const char*)(gbase) + (voff)[_i]), (PG8_LAS unsigned*)(lds + (bufoff) + ldsw + _i * 8192), 16, 0, 0); } while (0)
; #define PG8_LDA(dst, b, h) do { _Pragma("unroll") for (int m = 0; m < 4; ++m) _Pragma("unroll") for (int k = 0; k < 2; ++k) dst[m][k] = *(const PG8_LAS bf16x8*)(lds + PG8_SA(b, h) + aoff + m * 2048 + k * 1024); } while (0)
; #define PG8_MMA(ai, bj, At, Bt) do { __builtin_amdgcn_s_setprio(1); _Pragma("unroll") for (int m = 0; m < 4; ++m) _Pragma("unroll") for (int n = 0; n < 2; ++n) _Pragma("unroll") for (int k = 0; k < 2; ++k) \
;         acc[ai][bj][m][n] = __builtin_amdgcn_mfma_f32_16x16x32_bf16(Bt[n][k], At[m][k], acc[ai][bj][m][n], 0, 0, 0); __builtin_amdgcn_s_setprio(0); } while (0)
; #define PG8_WAIT_V(n) asm volatile("s_waitcnt vmcnt(" #n ")" ::: "memory")
; #define PG8_WAIT_L(n) asm volatile("s_waitcnt lgkmcnt(" #n ")" ::: "memory")
; #define PG8_BAR __builtin_amdgcn_s_barrier()
; #define PG8_SCHED __builtin_amdgcn_sched_barrier(0)
; template <class Epi, class Sched, bool ALIGN_EPI = false, bool SP2 = false>
; __device__ __forceinline__ void gemm_phase(PG8_LAS unsigned char* lds, const Gemm g, const Sched& S, const Epi& E) {
;     ...
;         for (int t = 0; t < nt; t += 2) {
;             const bool last = (t == nt - 2);
;             const char* a1 = cA + (size_t)(t + 1) * kstep;
;             const char* a2 = last ? nA : cA + (size_t)(t + 2) * kstep; const char* b2 = last ? nB : cB + (size_t)(t + 2) * kstep;
;             const char* a3 = a2 + kstep; const char* b3 = b2 + kstep;
;             if (last && has_next) S.a_ready(nxt);
;     ...
;             PG8_LDA(At, 1, 1); PG8_STAGE(PG8_SB(1, 0), b3, voffB); PG8_STAGE(PG8_SB(1, 1), b3 + hstepB, voffB); PG8_STAGE(PG8_SA(1, 0), a3, voffA);
;             PG8_WAIT_V(8); PG8_WAIT_L(0); PG8_BAR; PG8_MMA(1, 0, At, B0); PG8_MMA(1, 1, At, B1); PG8_BAR; PG8_SCHED;
	s_add_i32 s38, s57, s40
	v_lshl_add_u64 v[218:219], v[218:219], 0, s[12:13]
	s_mov_b32 m0, s38
	ds_read_b128 v[186:189], v178 offset:49152
	ds_read_b128 v[190:193], v178 offset:50176
	ds_read_b128 v[194:197], v178 offset:51200
	ds_read_b128 v[198:201], v178 offset:52224
	ds_read_b128 v[202:205], v178 offset:53248
	ds_read_b128 v[206:209], v178 offset:54272
	ds_read_b128 v[210:213], v178 offset:55296
	ds_read_b128 v[214:217], v178 offset:56320
	global_load_lds_dwordx4 v[218:219], off
	s_add_i32 m0, s38, 0x2000
	s_add_u32 s36, s36, 0x40080
	v_lshl_add_u64 v[218:219], v[220:221], 0, s[12:13]
	s_addc_u32 s37, s37, 0
	s_add_i32 s38, s58, s40
	global_load_lds_dwordx4 v[218:219], off
	v_lshl_add_u64 v[218:219], s[36:37], 0, v[146:147]
	s_mov_b32 m0, s38
	s_nop 0
	global_load_lds_dwordx4 v[218:219], off
	v_lshl_add_u64 v[218:219], s[36:37], 0, v[150:151]
	s_add_i32 m0, s38, 0x2000
	s_nop 0
	global_load_lds_dwordx4 v[218:219], off
	v_lshl_add_u64 v[218:219], v[222:223], 0, s[12:13]
	s_mov_b32 m0, s45
	s_nop 0
	global_load_lds_dwordx4 v[218:219], off
	v_lshl_add_u64 v[218:219], v[224:225], 0, s[12:13]
	s_mov_b32 m0, s46
	s_nop 0
	global_load_lds_dwordx4 v[218:219], off
	s_waitcnt vmcnt(8)
	s_waitcnt lgkmcnt(0)
	s_barrier
	s_nop 0
	s_waitcnt lgkmcnt(0)
	v_mfma_f32_16x16x32_bf16 v[60:63], v[128:131], v[186:189], v[60:63]
	v_mfma_f32_16x16x32_bf16 v[56:59], v[136:139], v[186:189], v[56:59]
	v_mfma_f32_16x16x32_bf16 v[44:47], v[128:131], v[194:197], v[44:47]
	v_mfma_f32_16x16x32_bf16 v[40:43], v[136:139], v[194:197], v[40:43]
	v_mfma_f32_16x16x32_bf16 v[28:31], v[128:131], v[202:205], v[28:31]
	v_mfma_f32_16x16x32_bf16 v[24:27], v[136:139], v[202:205], v[24:27]
	v_mfma_f32_16x16x32_bf16 v[12:15], v[128:131], v[210:213], v[12:15]
	v_mfma_f32_16x16x32_bf16 v[8:11], v[136:139], v[210:213], v[8:11]
	v_mfma_f32_16x16x32_bf16 v[60:63], v[132:135], v[190:193], v[60:63]
	v_mfma_f32_16x16x32_bf16 v[56:59], v[140:143], v[190:193], v[56:59]
	v_mfma_f32_16x16x32_bf16 v[44:47], v[132:135], v[198:201], v[44:47]
	v_mfma_f32_16x16x32_bf16 v[40:43], v[140:143], v[198:201], v[40:43]
	v_mfma_f32_16x16x32_bf16 v[28:31], v[132:135], v[206:209], v[28:31]
	v_mfma_f32_16x16x32_bf16 v[24:27], v[140:143], v[206:209], v[24:27]
	v_mfma_f32_16x16x32_bf16 v[12:15], v[132:135], v[214:217], v[12:15]
	v_mfma_f32_16x16x32_bf16 v[8:11], v[140:143], v[214:217], v[8:11]
	v_mfma_f32_16x16x32_bf16 v[52:55], v[162:165], v[186:189], v[52:55]
	v_mfma_f32_16x16x32_bf16 v[48:51], v[170:173], v[186:189], v[48:51]
	v_mfma_f32_16x16x32_bf16 v[36:39], v[162:165], v[194:197], v[36:39]
	v_mfma_f32_16x16x32_bf16 v[32:35], v[170:173], v[194:197], v[32:35]
	v_mfma_f32_16x16x32_bf16 v[20:23], v[162:165], v[202:205], v[20:23]
	v_mfma_f32_16x16x32_bf16 v[16:19], v[170:173], v[202:205], v[16:19]
	v_mfma_f32_16x16x32_bf16 v[4:7], v[162:165], v[210:213], v[4:7]
	v_mfma_f32_16x16x32_bf16 v[0:3], v[170:173], v[210:213], v[0:3]
	v_mfma_f32_16x16x32_bf16 v[52:55], v[166:169], v[190:193], v[52:55]
	v_mfma_f32_16x16x32_bf16 v[48:51], v[180:183], v[190:193], v[48:51]
	v_mfma_f32_16x16x32_bf16 v[36:39], v[166:169], v[198:201], v[36:39]
	v_mfma_f32_16x16x32_bf16 v[32:35], v[180:183], v[198:201], v[32:35]
	v_mfma_f32_16x16x32_bf16 v[20:23], v[166:169], v[206:209], v[20:23]
	v_mfma_f32_16x16x32_bf16 v[16:19], v[180:183], v[206:209], v[16:19]
	v_mfma_f32_16x16x32_bf16 v[4:7], v[166:169], v[214:217], v[4:7]
	v_mfma_f32_16x16x32_bf16 v[0:3], v[180:183], v[214:217], v[0:3]
	s_nop 0
	s_barrier
	s_add_i32 s56, s56, 2
	s_add_u32 s34, s34, 0x100
	s_addc_u32 s35, s35, 0
	s_add_u32 s54, s54, 0x100
	s_addc_u32 s55, s55, 0
	s_cmp_gt_u32 s56, 13
	s_cbranch_scc0 .LBB0_1007
	s_and_b64 vcc, exec, s[16:17]
	s_cbranch_vccz .LBB0_1010
	s_barrier

; #define PG8_STAGE(bufoff, gbase, voff) do { _Pragma("unroll") for (int _i = 0; _i < 2; ++_i) \
;         __builtin_amdgcn_global_load_lds((const unsigned*)((const char*)(gbase) + (voff)[_i]), (PG8_LAS unsigned*)(lds + (bufoff) + ldsw + _i * 8192), 16, 0, 0); } while (0)
; #define PG8_LDA(dst, b, h) do { _Pragma("unroll") for (int m = 0; m < 4; ++m) _Pragma("unroll") for (int k = 0; k < 2; ++k) dst[m][k] = *(const PG8_LAS bf16x8*)(lds + PG8_SA(b, h) + aoff + m * 2048 + k * 1024); } while (0)
; #define PG8_LDB(dst, b, h) do { _Pragma("unroll") for (int n = 0; n < 2; ++n) _Pragma("unroll") for (int k = 0; k < 2; ++k) dst[n][k] = *(const PG8_LAS bf16x8*)(lds + PG8_SB(b, h) + boff + n * 2048 + k * 1024); } while (0)
; #define PG8_MMA(ai, bj, At, Bt) do { __builtin_amdgcn_s_setprio(1); _Pragma("unroll") for (int m = 0; m < 4; ++m) _Pragma("unroll") for (int n = 0; n < 2; ++n) _Pragma("unroll") for (int k = 0; k < 2; ++k) \
;         acc[ai][bj][m][n] = __builtin_amdgcn_mfma_f32_16x16x32_bf16(Bt[n][k], At[m][k], acc[ai][bj][m][n], 0, 0, 0); __builtin_amdgcn_s_setprio(0); } while (0)
; #define PG8_WAIT_V(n) asm volatile("s_waitcnt vmcnt(" #n ")" ::: "memory")
; #define PG8_BAR __builtin_amdgcn_s_barrier()
; template <class Epi, class Sched, bool ALIGN_EPI = false, bool SP2 = false>
; __device__ __forceinline__ void gemm_phase(PG8_LAS unsigned char* lds, const Gemm g, const Sched& S, const Epi& E) {
;     ...
;         for (int t = 0; t < nt; t += 2) {
;             const bool last = (t == nt - 2);
;             const char* a1 = cA + (size_t)(t + 1) * kstep;
;             const char* a2 = last ? nA : cA + (size_t)(t + 2) * kstep; const char* b2 = last ? nB : cB + (size_t)(t + 2) * kstep;
;             const char* a3 = a2 + kstep; const char* b3 = b2 + kstep;
;             if (last && has_next) S.a_ready(nxt);
;             if constexpr (SP2) {
;             PG8_LDB(B0, 0, 0); PG8_LDB(B1, 0, 1); PG8_SCHED; PG8_LDA(At, 0, 0); PG8_STAGE(PG8_SA(1, 1), a1 + hstepA, voffA);
;             PG8_WAIT_V(8); PG8_WAIT_L(0); PG8_BAR; PG8_MMA(0, 0, At, B0); PG8_MMA(0, 1, At, B1); PG8_BAR; PG8_SCHED;
;             PG8_LDA(At, 0, 1); PG8_STAGE(PG8_SB(0, 0), b2, voffB); PG8_STAGE(PG8_SB(0, 1), b2 + hstepB, voffB); PG8_STAGE(PG8_SA(0, 0), a2, voffA);
;             PG8_WAIT_V(8); PG8_WAIT_L(0); PG8_BAR; PG8_MMA(1, 0, At, B0); PG8_MMA(1, 1, At, B1); PG8_BAR; PG8_SCHED;
.LBB0_1061:
	ds_read_b128 v[128:131], v199
	ds_read_b128 v[132:135], v199 offset:1024
	ds_read_b128 v[136:139], v199 offset:2048
	ds_read_b128 v[140:143], v199 offset:3072
	ds_read_b128 v[144:147], v200
	ds_read_b128 v[148:151], v200 offset:1024
	ds_read_b128 v[152:155], v200 offset:2048
	ds_read_b128 v[156:159], v200 offset:3072
	s_add_u32 s20, s18, 0xfff00080
	s_addc_u32 s21, s19, -1
	s_cmp_eq_u32 s45, 60
	s_cselect_b32 s23, s11, s21
	s_cselect_b32 s22, s41, s20
	s_cselect_b32 s21, s9, s44
	s_cselect_b32 s20, s42, s43
	v_lshl_add_u64 v[196:197], s[18:19], 0, v[180:181]
	s_add_i32 m0, s17, 0xc000
	ds_read_b128 v[160:163], v201
	ds_read_b128 v[164:167], v201 offset:1024
	ds_read_b128 v[188:191], v201 offset:2048
	ds_read_b128 v[192:195], v201 offset:3072
	ds_read_b128 v[202:205], v201 offset:4096
	ds_read_b128 v[206:209], v201 offset:5120
	ds_read_b128 v[210:213], v201 offset:6144
	ds_read_b128 v[214:217], v201 offset:7168
	global_load_lds_dwordx4 v[196:197], off
	v_lshl_add_u64 v[196:197], s[18:19], 0, v[182:183]
	s_add_i32 m0, s17, 0xe000
	s_nop 0
	global_load_lds_dwordx4 v[196:197], off
	s_waitcnt vmcnt(8)
	s_waitcnt lgkmcnt(0)
	s_barrier
	s_nop 0
	s_waitcnt lgkmcnt(0)
	v_mfma_f32_16x16x32_bf16 v[124:127], v[128:131], v[160:163], v[124:127]
	v_mfma_f32_16x16x32_bf16 v[120:123], v[136:139], v[160:163], v[120:123]
	v_mfma_f32_16x16x32_bf16 v[112:115], v[128:131], v[188:191], v[112:115]
	v_mfma_f32_16x16x32_bf16 v[104:107], v[136:139], v[188:191], v[104:107]
	v_mfma_f32_16x16x32_bf16 v[96:99], v[128:131], v[202:205], v[96:99]
	v_mfma_f32_16x16x32_bf16 v[88:91], v[136:139], v[202:205], v[88:91]
	v_mfma_f32_16x16x32_bf16 v[80:83], v[128:131], v[210:213], v[80:83]
	v_mfma_f32_16x16x32_bf16 v[72:75], v[136:139], v[210:213], v[72:75]
	v_mfma_f32_16x16x32_bf16 v[124:127], v[132:135], v[164:167], v[124:127]
	v_mfma_f32_16x16x32_bf16 v[120:123], v[140:143], v[164:167], v[120:123]
	v_mfma_f32_16x16x32_bf16 v[112:115], v[132:135], v[192:195], v[112:115]
	v_mfma_f32_16x16x32_bf16 v[104:107], v[140:143], v[192:195], v[104:107]
	v_mfma_f32_16x16x32_bf16 v[96:99], v[132:135], v[206:209], v[96:99]
	v_mfma_f32_16x16x32_bf16 v[88:91], v[140:143], v[206:209], v[88:91]
	v_mfma_f32_16x16x32_bf16 v[80:83], v[132:135], v[214:217], v[80:83]
	v_mfma_f32_16x16x32_bf16 v[72:75], v[140:143], v[214:217], v[72:75]
	v_mfma_f32_16x16x32_bf16 v[116:119], v[144:147], v[160:163], v[116:119]
	v_mfma_f32_16x16x32_bf16 v[108:111], v[152:155], v[160:163], v[108:111]
	v_mfma_f32_16x16x32_bf16 v[100:103], v[144:147], v[188:191], v[100:103]
	v_mfma_f32_16x16x32_bf16 v[92:95], v[152:155], v[188:191], v[92:95]
	v_mfma_f32_16x16x32_bf16 v[84:87], v[144:147], v[202:205], v[84:87]
	v_mfma_f32_16x16x32_bf16 v[76:79], v[152:155], v[202:205], v[76:79]
	v_mfma_f32_16x16x32_bf16 v[68:71], v[144:147], v[210:213], v[68:71]
	v_mfma_f32_16x16x32_bf16 v[64:67], v[152:155], v[210:213], v[64:67]
	v_mfma_f32_16x16x32_bf16 v[116:119], v[148:151], v[164:167], v[116:119]
	v_mfma_f32_16x16x32_bf16 v[108:111], v[156:159], v[164:167], v[108:111]
	v_mfma_f32_16x16x32_bf16 v[100:103], v[148:151], v[192:195], v[100:103]
	v_mfma_f32_16x16x32_bf16 v[92:95], v[156:159], v[192:195], v[92:95]
	v_mfma_f32_16x16x32_bf16 v[84:87], v[148:151], v[206:209], v[84:87]
	v_mfma_f32_16x16x32_bf16 v[76:79], v[156:159], v[206:209], v[76:79]
	v_mfma_f32_16x16x32_bf16 v[68:71], v[148:151], v[214:217], v[68:71]
	v_mfma_f32_16x16x32_bf16 v[64:67], v[156:159], v[214:217], v[64:67]
	s_nop 0
	s_barrier
	s_add_i32 s46, s38, s29
	v_lshl_add_u64 v[196:197], s[20:21], 0, v[170:171]
	s_mov_b32 m0, s46
	ds_read_b128 v[160:163], v201 offset:16384
	ds_read_b128 v[164:167], v201 offset:17408
	ds_read_b128 v[188:191], v201 offset:18432
	ds_read_b128 v[192:195], v201 offset:19456
	ds_read_b128 v[202:205], v201 offset:20480
	ds_read_b128 v[206:209], v201 offset:21504
	ds_read_b128 v[210:213], v201 offset:22528
	ds_read_b128 v[214:217], v201 offset:23552
	global_load_lds_dwordx4 v[196:197], off
	s_add_i32 m0, s46, 0x2000
	s_add_u32 s46, s20, 0x100000
	v_lshl_add_u64 v[218:219], s[20:21], 0, v[174:175]
	s_addc_u32 s47, s21, 0
	s_add_i32 s48, s39, s29
	global_load_lds_dwordx4 v[218:219], off
	v_lshl_add_u64 v[220:221], s[46:47], 0, v[170:171]
	s_mov_b32 m0, s48
	v_lshl_add_u64 v[222:223], s[22:23], 0, v[172:173]
	global_load_lds_dwordx4 v[220:221], off
	v_lshl_add_u64 v[220:221], s[46:47], 0, v[174:175]
	s_add_i32 m0, s48, 0x2000
	s_nop 0
	global_load_lds_dwordx4 v[220:221], off
	v_lshl_add_u64 v[220:221], s[22:23], 0, v[168:169]
	s_mov_b32 m0, s17
	s_nop 0
	global_load_lds_dwordx4 v[220:221], off
	s_mov_b32 m0, s30
	s_nop 0
	global_load_lds_dwordx4 v[222:223], off
	s_waitcnt vmcnt(8)
	s_waitcnt lgkmcnt(0)
	s_barrier
; #define PG8_STAGE(bufoff, gbase, voff) do { _Pragma("unroll") for (int _i = 0; _i < 2; ++_i) \
;         __builtin_amdgcn_global_load_lds((const unsigned*)((const char*)(gbase) + (voff)[_i]), (PG8_LAS unsigned*)(lds + (bufoff) + ldsw + _i * 8192), 16, 0, 0); } while (0)
; #define PG8_LDA(dst, b, h) do { _Pragma("unroll") for (int m = 0; m < 4; ++m) _Pragma("unroll") for (int k = 0; k < 2; ++k) dst[m][k] = *(const PG8_LAS bf16x8*)(lds + PG8_SA(b, h) + aoff + m * 2048 + k * 1024); } while (0)
; #define PG8_LDB(dst, b, h) do { _Pragma("unroll") for (int n = 0; n < 2; ++n) _Pragma("unroll") for (int k = 0; k < 2; ++k) dst[n][k] = *(const PG8_LAS bf16x8*)(lds + PG8_SB(b, h) + boff + n * 2048 + k * 1024); } while (0)
; #define PG8_MMA(ai, bj, At, Bt) do { __builtin_amdgcn_s_setprio(1); _Pragma("unroll") for (int m = 0; m < 4; ++m) _Pragma("unroll") for (int n = 0; n < 2; ++n) _Pragma("unroll") for (int k = 0; k < 2; ++k) \
;         acc[ai][bj][m][n] = __builtin_amdgcn_mfma_f32_16x16x32_bf16(Bt[n][k], At[m][k], acc[ai][bj][m][n], 0, 0, 0); __builtin_amdgcn_s_setprio(0); } while (0)
; #define PG8_WAIT_V(n) asm volatile("s_waitcnt vmcnt(" #n ")" ::: "memory")
; #define PG8_WAIT_L(n) asm volatile("s_waitcnt lgkmcnt(" #n ")" ::: "memory")
; #define PG8_BAR __builtin_amdgcn_s_barrier()
; #define PG8_SCHED __builtin_amdgcn_sched_barrier(0)
; template <class Epi, class Sched, bool ALIGN_EPI = false, bool SP2 = false>
; __device__ __forceinline__ void gemm_phase(PG8_LAS unsigned char* lds, const Gemm g, const Sched& S, const Epi& E) {
;     ...
;             PG8_WAIT_V(8); PG8_WAIT_L(0); PG8_BAR; PG8_MMA(1, 0, At, B0); PG8_MMA(1, 1, At, B1); PG8_BAR; PG8_SCHED;
;             PG8_LDB(B0, 1, 0); PG8_LDB(B1, 1, 1); PG8_SCHED; PG8_LDA(At, 1, 0); PG8_STAGE(PG8_SA(0, 1), a2 + hstepA, voffA);
;             PG8_WAIT_V(8); PG8_WAIT_L(0); PG8_BAR; PG8_MMA(0, 0, At, B0); PG8_MMA(0, 1, At, B1); PG8_BAR; PG8_SCHED;
	s_nop 0
	s_waitcnt lgkmcnt(0)
	v_mfma_f32_16x16x32_bf16 v[60:63], v[128:131], v[160:163], v[60:63]
	v_mfma_f32_16x16x32_bf16 v[56:59], v[136:139], v[160:163], v[56:59]
	v_mfma_f32_16x16x32_bf16 v[48:51], v[128:131], v[188:191], v[48:51]
	v_mfma_f32_16x16x32_bf16 v[40:43], v[136:139], v[188:191], v[40:43]
	v_mfma_f32_16x16x32_bf16 v[32:35], v[128:131], v[202:205], v[32:35]
	v_mfma_f32_16x16x32_bf16 v[24:27], v[136:139], v[202:205], v[24:27]
	v_mfma_f32_16x16x32_bf16 v[16:19], v[128:131], v[210:213], v[16:19]
	v_mfma_f32_16x16x32_bf16 v[8:11], v[136:139], v[210:213], v[8:11]
	v_mfma_f32_16x16x32_bf16 v[60:63], v[132:135], v[164:167], v[60:63]
	v_mfma_f32_16x16x32_bf16 v[56:59], v[140:143], v[164:167], v[56:59]
	v_mfma_f32_16x16x32_bf16 v[48:51], v[132:135], v[192:195], v[48:51]
	v_mfma_f32_16x16x32_bf16 v[40:43], v[140:143], v[192:195], v[40:43]
	v_mfma_f32_16x16x32_bf16 v[32:35], v[132:135], v[206:209], v[32:35]
	v_mfma_f32_16x16x32_bf16 v[24:27], v[140:143], v[206:209], v[24:27]
	v_mfma_f32_16x16x32_bf16 v[16:19], v[132:135], v[214:217], v[16:19]
	v_mfma_f32_16x16x32_bf16 v[8:11], v[140:143], v[214:217], v[8:11]
	v_mfma_f32_16x16x32_bf16 v[52:55], v[144:147], v[160:163], v[52:55]
	v_mfma_f32_16x16x32_bf16 v[44:47], v[152:155], v[160:163], v[44:47]
	v_mfma_f32_16x16x32_bf16 v[36:39], v[144:147], v[188:191], v[36:39]
	v_mfma_f32_16x16x32_bf16 v[28:31], v[152:155], v[188:191], v[28:31]
	v_mfma_f32_16x16x32_bf16 v[20:23], v[144:147], v[202:205], v[20:23]
	v_mfma_f32_16x16x32_bf16 v[12:15], v[152:155], v[202:205], v[12:15]
	v_mfma_f32_16x16x32_bf16 v[4:7], v[144:147], v[210:213], v[4:7]
	v_mfma_f32_16x16x32_bf16 v[0:3], v[152:155], v[210:213], v[0:3]
	v_mfma_f32_16x16x32_bf16 v[52:55], v[148:151], v[164:167], v[52:55]
	v_mfma_f32_16x16x32_bf16 v[44:47], v[156:159], v[164:167], v[44:47]
	v_mfma_f32_16x16x32_bf16 v[36:39], v[148:151], v[192:195], v[36:39]
	v_mfma_f32_16x16x32_bf16 v[28:31], v[156:159], v[192:195], v[28:31]
	v_mfma_f32_16x16x32_bf16 v[20:23], v[148:151], v[206:209], v[20:23]
	v_mfma_f32_16x16x32_bf16 v[12:15], v[156:159], v[206:209], v[12:15]
	v_mfma_f32_16x16x32_bf16 v[4:7], v[148:151], v[214:217], v[4:7]
	v_mfma_f32_16x16x32_bf16 v[0:3], v[156:159], v[214:217], v[0:3]
	s_nop 0
	s_barrier
	s_add_i32 s46, 0, 0x18000
	s_add_i32 s47, 0, 0x1c000
	v_add_u32_e32 v140, s46, v198
	v_add_u32_e32 v156, s47, v198
	ds_read_b128 v[128:131], v140
	ds_read_b128 v[132:135], v140 offset:1024
	ds_read_b128 v[136:139], v140 offset:2048
	ds_read_b128 v[140:143], v140 offset:3072
	ds_read_b128 v[144:147], v156
	ds_read_b128 v[148:151], v156 offset:1024
	ds_read_b128 v[152:155], v156 offset:2048
	ds_read_b128 v[156:159], v156 offset:3072
	s_add_u32 s22, s22, 0x100000
	s_addc_u32 s23, s23, 0
	s_mov_b32 m0, s31
	v_lshl_add_u64 v[224:225], s[22:23], 0, v[168:169]
	ds_read_b128 v[160:163], v201 offset:32768
	ds_read_b128 v[164:167], v201 offset:33792
	ds_read_b128 v[188:191], v201 offset:34816
	ds_read_b128 v[192:195], v201 offset:35840
	ds_read_b128 v[202:205], v201 offset:36864
	ds_read_b128 v[206:209], v201 offset:37888
	ds_read_b128 v[210:213], v201 offset:38912
	ds_read_b128 v[214:217], v201 offset:39936
	global_load_lds_dwordx4 v[224:225], off
	v_lshl_add_u64 v[224:225], s[22:23], 0, v[172:173]
	s_mov_b32 m0, s33
	s_nop 0
	global_load_lds_dwordx4 v[224:225], off
	s_waitcnt vmcnt(8)
	s_waitcnt lgkmcnt(0)
	s_barrier
	s_nop 0
	s_waitcnt lgkmcnt(0)
	v_mfma_f32_16x16x32_bf16 v[124:127], v[128:131], v[160:163], v[124:127]
	v_mfma_f32_16x16x32_bf16 v[120:123], v[136:139], v[160:163], v[120:123]
	v_mfma_f32_16x16x32_bf16 v[112:115], v[128:131], v[188:191], v[112:115]
	v_mfma_f32_16x16x32_bf16 v[104:107], v[136:139], v[188:191], v[104:107]
	v_mfma_f32_16x16x32_bf16 v[96:99], v[128:131], v[202:205], v[96:99]
	v_mfma_f32_16x16x32_bf16 v[88:91], v[136:139], v[202:205], v[88:91]
	v_mfma_f32_16x16x32_bf16 v[80:83], v[128:131], v[210:213], v[80:83]
	v_mfma_f32_16x16x32_bf16 v[72:75], v[136:139], v[210:213], v[72:75]
	v_mfma_f32_16x16x32_bf16 v[124:127], v[132:135], v[164:167], v[124:127]
	v_mfma_f32_16x16x32_bf16 v[120:123], v[140:143], v[164:167], v[120:123]
	v_mfma_f32_16x16x32_bf16 v[112:115], v[132:135], v[192:195], v[112:115]
	v_mfma_f32_16x16x32_bf16 v[104:107], v[140:143], v[192:195], v[104:107]
	v_mfma_f32_16x16x32_bf16 v[96:99], v[132:135], v[206:209], v[96:99]
	v_mfma_f32_16x16x32_bf16 v[88:91], v[140:143], v[206:209], v[88:91]
	v_mfma_f32_16x16x32_bf16 v[80:83], v[132:135], v[214:217], v[80:83]
	v_mfma_f32_16x16x32_bf16 v[72:75], v[140:143], v[214:217], v[72:75]
	v_mfma_f32_16x16x32_bf16 v[116:119], v[144:147], v[160:163], v[116:119]
	v_mfma_f32_16x16x32_bf16 v[108:111], v[152:155], v[160:163], v[108:111]
	v_mfma_f32_16x16x32_bf16 v[100:103], v[144:147], v[188:191], v[100:103]
	v_mfma_f32_16x16x32_bf16 v[92:95], v[152:155], v[188:191], v[92:95]
	v_mfma_f32_16x16x32_bf16 v[84:87], v[144:147], v[202:205], v[84:87]
	v_mfma_f32_16x16x32_bf16 v[76:79], v[152:155], v[202:205], v[76:79]
	v_mfma_f32_16x16x32_bf16 v[68:71], v[144:147], v[210:213], v[68:71]
	v_mfma_f32_16x16x32_bf16 v[64:67], v[152:155], v[210:213], v[64:67]
	v_mfma_f32_16x16x32_bf16 v[116:119], v[148:151], v[164:167], v[116:119]
	v_mfma_f32_16x16x32_bf16 v[108:111], v[156:159], v[164:167], v[108:111]
	v_mfma_f32_16x16x32_bf16 v[100:103], v[148:151], v[192:195], v[100:103]
	v_mfma_f32_16x16x32_bf16 v[92:95], v[156:159], v[192:195], v[92:95]
	v_mfma_f32_16x16x32_bf16 v[84:87], v[148:151], v[206:209], v[84:87]
	v_mfma_f32_16x16x32_bf16 v[76:79], v[156:159], v[206:209], v[76:79]
	v_mfma_f32_16x16x32_bf16 v[68:71], v[148:151], v[214:217], v[68:71]
	v_mfma_f32_16x16x32_bf16 v[64:67], v[156:159], v[214:217], v[64:67]
	s_nop 0
	s_barrier
; #define PG8_STAGE(bufoff, gbase, voff) do { _Pragma("unroll") for (int _i = 0; _i < 2; ++_i) \
;         __builtin_amdgcn_global_load_lds((const unsigned*)((const char*)(gbase) + (voff)[_i]), (PG8_LAS unsigned*)(lds + (bufoff) + ldsw + _i * 8192), 16, 0, 0); } while (0)
; #define PG8_LDA(dst, b, h) do { _Pragma("unroll") for (int m = 0; m < 4; ++m) _Pragma("unroll") for (int k = 0; k < 2; ++k) dst[m][k] = *(const PG8_LAS bf16x8*)(lds + PG8_SA(b, h) + aoff + m * 2048 + k * 1024); } while (0)
; #define PG8_MMA(ai, bj, At, Bt) do { __builtin_amdgcn_s_setprio(1); _Pragma("unroll") for (int m = 0; m < 4; ++m) _Pragma("unroll") for (int n = 0; n < 2; ++n) _Pragma("unroll") for (int k = 0; k < 2; ++k) \
;         acc[ai][bj][m][n] = __builtin_amdgcn_mfma_f32_16x16x32_bf16(Bt[n][k], At[m][k], acc[ai][bj][m][n], 0, 0, 0); __builtin_amdgcn_s_setprio(0); } while (0)
; #define PG8_WAIT_V(n) asm volatile("s_waitcnt vmcnt(" #n ")" ::: "memory")
; #define PG8_WAIT_L(n) asm volatile("s_waitcnt lgkmcnt(" #n ")" ::: "memory")
; #define PG8_BAR __builtin_amdgcn_s_barrier()
; #define PG8_SCHED __builtin_amdgcn_sched_barrier(0)
; template <class Epi, class Sched, bool ALIGN_EPI = false, bool SP2 = false>
; __device__ __forceinline__ void gemm_phase(PG8_LAS unsigned char* lds, const Gemm g, const Sched& S, const Epi& E) {
;     ...
;         for (int t = 0; t < nt; t += 2) {
;             const bool last = (t == nt - 2);
;             const char* a1 = cA + (size_t)(t + 1) * kstep;
;             const char* a2 = last ? nA : cA + (size_t)(t + 2) * kstep; const char* b2 = last ? nB : cB + (size_t)(t + 2) * kstep;
;             const char* a3 = a2 + kstep; const char* b3 = b2 + kstep;
;             if (last && has_next) S.a_ready(nxt);
;     ...
;             PG8_LDA(At, 1, 1); PG8_STAGE(PG8_SB(1, 0), b3, voffB); PG8_STAGE(PG8_SB(1, 1), b3 + hstepB, voffB); PG8_STAGE(PG8_SA(1, 0), a3, voffA);
;             PG8_WAIT_V(8); PG8_WAIT_L(0); PG8_BAR; PG8_MMA(1, 0, At, B0); PG8_MMA(1, 1, At, B1); PG8_BAR; PG8_SCHED;
	s_add_i32 s22, s46, s29
	v_lshl_add_u64 v[196:197], v[196:197], 0, s[4:5]
	s_mov_b32 m0, s22
	ds_read_b128 v[160:163], v201 offset:49152
	ds_read_b128 v[164:167], v201 offset:50176
	ds_read_b128 v[188:191], v201 offset:51200
	ds_read_b128 v[192:195], v201 offset:52224
	ds_read_b128 v[202:205], v201 offset:53248
	ds_read_b128 v[206:209], v201 offset:54272
	ds_read_b128 v[210:213], v201 offset:55296
	ds_read_b128 v[214:217], v201 offset:56320
	global_load_lds_dwordx4 v[196:197], off
	s_add_i32 m0, s22, 0x2000
	s_add_u32 s20, s20, 0x100080
	v_lshl_add_u64 v[196:197], v[218:219], 0, s[4:5]
	s_addc_u32 s21, s21, 0
	s_add_i32 s22, s47, s29
	global_load_lds_dwordx4 v[196:197], off
	v_lshl_add_u64 v[196:197], s[20:21], 0, v[170:171]
	s_mov_b32 m0, s22
	s_nop 0
	global_load_lds_dwordx4 v[196:197], off
	v_lshl_add_u64 v[196:197], s[20:21], 0, v[174:175]
	s_add_i32 m0, s22, 0x2000
	s_nop 0
	global_load_lds_dwordx4 v[196:197], off
	v_lshl_add_u64 v[196:197], v[220:221], 0, s[4:5]
	s_mov_b32 m0, s35
	s_nop 0
	global_load_lds_dwordx4 v[196:197], off
	v_lshl_add_u64 v[196:197], v[222:223], 0, s[4:5]
	s_mov_b32 m0, s36
	s_nop 0
	global_load_lds_dwordx4 v[196:197], off
	s_waitcnt vmcnt(8)
	s_waitcnt lgkmcnt(0)
	s_barrier
	s_nop 0
	s_waitcnt lgkmcnt(0)
	v_mfma_f32_16x16x32_bf16 v[60:63], v[128:131], v[160:163], v[60:63]
	v_mfma_f32_16x16x32_bf16 v[56:59], v[136:139], v[160:163], v[56:59]
	v_mfma_f32_16x16x32_bf16 v[48:51], v[128:131], v[188:191], v[48:51]
	v_mfma_f32_16x16x32_bf16 v[40:43], v[136:139], v[188:191], v[40:43]
	v_mfma_f32_16x16x32_bf16 v[32:35], v[128:131], v[202:205], v[32:35]
	v_mfma_f32_16x16x32_bf16 v[24:27], v[136:139], v[202:205], v[24:27]
	v_mfma_f32_16x16x32_bf16 v[16:19], v[128:131], v[210:213], v[16:19]
	v_mfma_f32_16x16x32_bf16 v[8:11], v[136:139], v[210:213], v[8:11]
	v_mfma_f32_16x16x32_bf16 v[60:63], v[132:135], v[164:167], v[60:63]
	v_mfma_f32_16x16x32_bf16 v[56:59], v[140:143], v[164:167], v[56:59]
	v_mfma_f32_16x16x32_bf16 v[48:51], v[132:135], v[192:195], v[48:51]
	v_mfma_f32_16x16x32_bf16 v[40:43], v[140:143], v[192:195], v[40:43]
	v_mfma_f32_16x16x32_bf16 v[32:35], v[132:135], v[206:209], v[32:35]
	v_mfma_f32_16x16x32_bf16 v[24:27], v[140:143], v[206:209], v[24:27]
	v_mfma_f32_16x16x32_bf16 v[16:19], v[132:135], v[214:217], v[16:19]
	v_mfma_f32_16x16x32_bf16 v[8:11], v[140:143], v[214:217], v[8:11]
	v_mfma_f32_16x16x32_bf16 v[52:55], v[144:147], v[160:163], v[52:55]
	v_mfma_f32_16x16x32_bf16 v[44:47], v[152:155], v[160:163], v[44:47]
	v_mfma_f32_16x16x32_bf16 v[36:39], v[144:147], v[188:191], v[36:39]
	v_mfma_f32_16x16x32_bf16 v[28:31], v[152:155], v[188:191], v[28:31]
	v_mfma_f32_16x16x32_bf16 v[20:23], v[144:147], v[202:205], v[20:23]
	v_mfma_f32_16x16x32_bf16 v[12:15], v[152:155], v[202:205], v[12:15]
	v_mfma_f32_16x16x32_bf16 v[4:7], v[144:147], v[210:213], v[4:7]
	v_mfma_f32_16x16x32_bf16 v[0:3], v[152:155], v[210:213], v[0:3]
	v_mfma_f32_16x16x32_bf16 v[52:55], v[148:151], v[164:167], v[52:55]
	v_mfma_f32_16x16x32_bf16 v[44:47], v[156:159], v[164:167], v[44:47]
	v_mfma_f32_16x16x32_bf16 v[36:39], v[148:151], v[192:195], v[36:39]
	v_mfma_f32_16x16x32_bf16 v[28:31], v[156:159], v[192:195], v[28:31]
	v_mfma_f32_16x16x32_bf16 v[20:23], v[148:151], v[206:209], v[20:23]
	v_mfma_f32_16x16x32_bf16 v[12:15], v[156:159], v[206:209], v[12:15]
	v_mfma_f32_16x16x32_bf16 v[4:7], v[148:151], v[214:217], v[4:7]
	v_mfma_f32_16x16x32_bf16 v[0:3], v[156:159], v[214:217], v[0:3]
	s_nop 0
	s_barrier
	s_add_i32 s45, s45, 2
	s_add_u32 s18, s18, 0x100
	s_addc_u32 s19, s19, 0
	s_add_u32 s43, s43, 0x100
	s_addc_u32 s44, s44, 0
	s_cmp_gt_u32 s45, 61
	s_cbranch_scc0 .LBB0_1061
	s_and_b64 vcc, exec, s[6:7]
	s_cbranch_vccz .LBB0_1064
	s_barrier
